# H (up-GEMM output / down-GEMM A operand) stored K-tile-blocked [panel][ktile][256 rows][64 cols] instead of row-major: contiguous epilogue stores in P4, contiguous A reads in P5
# speedup vs baseline: 1.0218x; 1.0065x over previous
;     __device__ __forceinline__ void operator()(const f32x4 (&acc)[2][2][4][2], const Unit& u, int wr, int wc, int fr, int fq) const {
;         const int row0 = u.pm * BM + wr * 64 + fr; const int col0 = u.pn * BM + wc * 32 + 8 * fq;
; template <class Epi, class Sched, bool ALIGN_EPI = false, bool SP2 = false>
; __device__ __forceinline__ void gemm_phase(PG8_LAS unsigned char* lds, const Gemm g, const Sched& S, const Epi& E) {
;     const int tid = threadIdx.x, wid = __builtin_amdgcn_readfirstlane(tid >> 6), lane = tid & 63, wr = wid >> 2, wc = wid & 3, fr = lane & 15, fq = lane >> 4;
;     const int K = g.K, nt = K / BK;
;     unsigned voffA[2], voffB[2];
; #pragma unroll
;     for (int i = 0; i < 2; ++i) { int R, C; stage_rc(tid * 16 + i * 8192, R, C); const int Rb = Epi::PERM ? ((R & ~31) + perm32(R & 31)) : R;
;         voffA[i] = (unsigned)(R * K + C) * 2u; voffB[i] = (unsigned)(Rb * K + C) * 2u; }
;     const size_t kstep = (size_t)(BK * 2);
;     const size_t hstep = (size_t)HALF * K * 2;
;     const size_t tstep = 2 * hstep;
;     const unsigned ldsw = (unsigned)wid * 1024u;
;     const int aoff = lds_byte(wr * 64 + fr, fq * 8), boff = lds_byte(wc * 32 + fr, fq * 8);
.LBB0_1373:
	s_lshl_b32 s0, s10, 5
	s_mov_b64 s[10:11], 0x80
	s_and_b32 s17, s0, 0x60
	s_and_b32 s100, s17, 32
	s_and_b32 s101, s17, 64
	s_lshl_b32 s101, s101, 8
	s_or_b32 s100, s100, s101
	s_mov_b64 s[58:59], 0x10000
	s_add_i32 m0, s34, 0x18000
	v_lshl_add_u64 v[8:9], v[8:9], 0, s[10:11]
	s_lshl_b32 s13, s14, 13
	s_lshl_b32 s18, s17, 7
	s_waitcnt vmcnt(2)
	s_barrier
	global_load_lds_dwordx4 v[8:9], off
	v_lshl_add_u64 v[4:5], v[4:5], 0, s[10:11]
	s_add_i32 m0, s34, 0x1a000
	s_add_i32 s38, s34, 0x8000
	s_add_i32 s39, s34, 0xa000
	global_load_lds_dwordx4 v[4:5], off
	v_lshl_add_u64 v[2:3], v[2:3], 0, s[10:11]
	s_mov_b32 m0, s38
	s_add_u32 s0, s26, 0x40080
	global_load_lds_dwordx4 v[2:3], off
	v_lshl_add_u64 v[2:3], v[6:7], 0, s[10:11]
	s_mov_b32 m0, s39
	s_addc_u32 s1, s27, 0
	global_load_lds_dwordx4 v[2:3], off
	s_add_i32 m0, s34, 0x1c000
	v_lshl_add_u64 v[2:3], s[0:1], 0, v[132:133]
	global_load_lds_dwordx4 v[2:3], off
	v_lshl_add_u64 v[2:3], s[0:1], 0, v[136:137]
	s_add_i32 m0, s34, 0x1e000
	v_bfe_u32 v4, v208, 4, 2
	global_load_lds_dwordx4 v[2:3], off
	v_and_b32_e32 v3, 15, v208
	v_lshlrev_b32_e32 v2, 4, v4
	v_lshlrev_b32_e32 v6, 2, v3
	v_lshl_or_b32 v1, s14, 6, v3
	v_lshl_or_b32 v5, v3, 6, v2
	v_and_b32_e32 v3, 32, v6
	v_bitop3_b32 v5, v5, s13, v3 bitop3:0xde
	v_lshlrev_b32_e32 v3, 6, v208
	s_movk_i32 s0, 0x3c0
	v_lshlrev_b32_e32 v7, 2, v208
	v_and_or_b32 v3, v3, s0, v2
	v_and_b32_e32 v7, 32, v7
	v_bitop3_b32 v7, s18, v3, v7 bitop3:0xf6
	v_mov_b32_e32 v3, v133
	v_lshl_add_u64 v[138:139], s[8:9], 0, v[2:3]
	v_lshlrev_b32_e32 v2, 8, v208
	v_and_b32_e32 v2, 0x38000, v2
	v_lshlrev_b32_e32 v3, 11, v12
	v_or3_b32 v2, v10, v2, v3
	s_cmpk_lt_u32 s12, 0x100
	v_add_u32_e32 v140, v2, v11
	v_lshlrev_b32_e32 v2, 4, v13
	s_cselect_b64 s[12:13], -1, 0
	s_lshl_b32 s8, s14, 8
	v_and_b32_e32 v2, 0x78000, v2
	s_mov_b32 s0, 0x18000
	s_mov_b32 s1, 0x1c000
	s_waitcnt vmcnt(6)
	s_addk_i32 s8, 0x100
	v_or3_b32 v2, v10, v2, v3
	s_add_i32 s8, s8, 0x20800
	v_add_u32_e32 v142, v2, v11
	s_add_i32 s41, s15, 0x100
	s_add_i32 s44, s16, 0x100
	s_add_i32 s45, s0, 0x100
	s_add_i32 s46, s1, 0x100
	v_mbcnt_lo_u32_b32 v2, -1, 0
	v_add_u32_e32 v151, s8, v6
	v_lshl_or_b32 v152, v4, 3, s100
	v_mov_b32_e32 v141, v133
	v_mov_b32_e32 v143, v133
	s_mov_b32 s23, 0
	s_movk_i32 s40, 0x181
	v_add_u32_e32 v153, s41, v7
	v_add_u32_e32 v154, s44, v7
	v_add_u32_e32 v155, 0x100, v5
	v_mov_b32_e32 v156, 0x358637bd
	v_mov_b64_e32 v[144:145], 0xbff
	v_add_u32_e32 v157, s45, v7
	v_add_u32_e32 v158, s46, v7
	v_mbcnt_hi_u32_b32 v159, -1, v2
	s_mov_b32 s47, 0
	s_barrier
	s_branch .LBB0_1376

;     __device__ __forceinline__ void operator()(const f32x4 (&acc)[2][2][4][2], const Unit& u, int wr, int wc, int fr, int fq) const {
;         const int row0 = u.pm * BM + wr * 64 + fr; const int col0 = u.pn * BM + wc * 32 + 8 * fq;
; #pragma unroll
;         for (int ai = 0; ai < 2; ++ai)
; #pragma unroll
;             for (int m = 0; m < 4; ++m) { const int r = row0 + ai * HALF + m * 16;
;                 float rstd;
;                 if (u.idx < UP_TAB_ROUNDS) rstd = tab[u.idx * BM + ai * HALF + wr * 64 + m * 16 + fr];
;                 else { const f32x4 p = *(const f32x4*)(stats + (size_t)r * 16 + 4 * fq); float s = (p[0] + p[1]) + (p[2] + p[3]);
;                     s += __shfl_xor(s, 16); s += __shfl_xor(s, 32); rstd = __builtin_amdgcn_rsqf(s * (1.0f / 1024.0f) + RMS_EPS); }
.LBB0_1383:
	s_mul_i32 s56, s24, 0x1f8000
	s_lshl_b32 s57, s22, 17
	s_add_u32 s56, s56, s57
	s_add_u32 s56, s50, s56
	s_addc_u32 s57, s51, 0
	s_cmp_gt_i32 s23, 11
	v_lshl_add_u32 v146, s24, 8, v1
	s_cselect_b64 s[24:25], -1, 0
	s_mov_b64 s[4:5], -1
	s_and_b64 vcc, exec, s[24:25]
	v_ashrrev_i32_e32 v147, 31, v146
	s_cbranch_vccz .LBB0_1385
	v_lshlrev_b64 v[148:149], 6, v[146:147]
	v_lshl_add_u64 v[148:149], v[138:139], 0, v[148:149]
	global_load_dwordx4 v[160:163], v[148:149], off
	v_and_b32_e32 v149, 64, v159
	v_xor_b32_e32 v148, 16, v159
	v_add_u32_e32 v150, 64, v149
	v_cmp_lt_i32_e32 vcc, v148, v150
	s_mov_b64 s[4:5], 0
	s_waitcnt vmcnt(0)
	v_mov_b32_e32 v149, v162
	v_cndmask_b32_e32 v148, v159, v148, vcc
	v_lshlrev_b32_e32 v164, 2, v148
	v_mov_b32_e32 v148, v161
	v_mov_b32_e32 v161, v163
	v_pk_add_f32 v[148:149], v[148:149], v[160:161]
	v_xor_b32_e32 v160, 32, v159
	v_add_f32_e32 v148, v148, v149
	ds_bpermute_b32 v149, v164, v148
	v_cmp_lt_i32_e32 vcc, v160, v150
	s_waitcnt lgkmcnt(0)
	v_add_f32_e32 v148, v148, v149
	v_cndmask_b32_e32 v150, v159, v160, vcc
	v_lshlrev_b32_e32 v149, 2, v150
	ds_bpermute_b32 v149, v149, v148
	s_waitcnt lgkmcnt(0)
	v_add_f32_e32 v148, v148, v149
	v_fmamk_f32 v148, v148, 0x3a800000, v156
	v_rsq_f32_e32 v150, v148

; __device__ __forceinline__ unsigned cvt_pk_bf16(float lo, float hi) { unsigned r; asm volatile("v_cvt_pk_bf16_f32 %0, %1, %2" : "=v"(r) : "v"(lo), "v"(hi)); return r; }
;     __device__ __forceinline__ void operator()(const f32x4 (&acc)[2][2][4][2], const Unit& u, int wr, int wc, int fr, int fq) const {
;     ...
;             for (int m = 0; m < 4; ++m) { const int r = row0 + ai * HALF + m * 16;
;                 float rstd;
;                 if (u.idx < UP_TAB_ROUNDS) rstd = tab[u.idx * BM + ai * HALF + wr * 64 + m * 16 + fr];
;                 else { const f32x4 p = *(const f32x4*)(stats + (size_t)r * 16 + 4 * fq); float s = (p[0] + p[1]) + (p[2] + p[3]);
;                     s += __shfl_xor(s, 16); s += __shfl_xor(s, 32); rstd = __builtin_amdgcn_rsqf(s * (1.0f / 1024.0f) + RMS_EPS); }
;                 bf16_t* rowp = H + (size_t)r * 4096 + col0;
; #pragma unroll
;                 for (int bj = 0; bj < 2; ++bj) { f32x4 v0 = acc[ai][bj][m][0] * rstd, v1 = acc[ai][bj][m][1] * rstd;
; #pragma unroll
;                     for (int e = 0; e < 4; ++e) { const float a = fmaxf(v0[e], 0.f), b = fmaxf(v1[e], 0.f); v0[e] = a * a; v1[e] = b * b; }
;                     u32x4 w; w.x = cvt_pk_bf16(v0[0], v0[1]); w.y = cvt_pk_bf16(v0[2], v0[3]); w.z = cvt_pk_bf16(v1[0], v1[1]); w.w = cvt_pk_bf16(v1[2], v1[3]);
;                     __builtin_nontemporal_store(w, (u32x4*)(rowp + bj * HALF)); } }
.LBB0_1387:
	s_waitcnt lgkmcnt(0)
	v_pk_mul_f32 v[122:123], v[122:123], v[150:151] op_sel_hi:[1,0]
	v_pk_mul_f32 v[126:127], v[126:127], v[150:151] op_sel_hi:[1,0]
	v_pk_mul_f32 v[124:125], v[124:125], v[150:151] op_sel_hi:[1,0]
	v_max_f32_e32 v122, 0, v122
	v_mov_b32_e32 v148, v152
	v_lshlrev_b64 v[162:163], 7, v[146:147]
	v_pk_mul_f32 v[128:129], v[128:129], v[150:151] op_sel_hi:[1,0]
	v_mul_f32_e32 v147, v122, v122
	v_max_f32_e32 v122, 0, v127
	v_max_f32_e32 v123, 0, v123
	v_max_f32_e32 v124, 0, v124
	v_ashrrev_i32_e32 v149, 31, v148
	v_lshl_add_u64 v[162:163], s[56:57], 0, v[162:163]
	v_max_f32_e32 v126, 0, v126
	v_mul_f32_e32 v122, v122, v122
	v_mul_f32_e32 v127, v123, v123
	v_max_f32_e32 v123, 0, v128
	v_mul_f32_e32 v128, v124, v124
	v_max_f32_e32 v124, 0, v129
	v_max_f32_e32 v125, 0, v125
	v_pk_mul_f32 v[116:117], v[116:117], v[150:151] op_sel_hi:[1,0]
	v_pk_mul_f32 v[114:115], v[114:115], v[150:151] op_sel_hi:[1,0]
	v_lshl_add_u64 v[162:163], v[148:149], 1, v[162:163]
	v_mul_f32_e32 v126, v126, v126
	v_mul_f32_e32 v123, v123, v123
	v_mul_f32_e32 v124, v124, v124
	v_mul_f32_e32 v125, v125, v125
	v_cvt_pk_bf16_f32 v122, v126, v122
	v_pk_mul_f32 v[120:121], v[120:121], v[150:151] op_sel_hi:[1,0]
	v_pk_mul_f32 v[118:119], v[118:119], v[150:151] op_sel_hi:[1,0]
	v_max_f32_e32 v114, 0, v114
	v_max_f32_e32 v115, 0, v115
	v_max_f32_e32 v116, 0, v116
	v_cvt_pk_bf16_f32 v123, v123, v124
	v_cvt_pk_bf16_f32 v124, v147, v127
	v_cvt_pk_bf16_f32 v125, v128, v125
	global_store_dwordx4 v[162:163], v[122:125], off nt
	v_max_f32_e32 v118, 0, v118
	v_max_f32_e32 v117, 0, v117
	v_mul_f32_e32 v122, v114, v114
	v_max_f32_e32 v114, 0, v119
	v_mul_f32_e32 v119, v115, v115
	v_max_f32_e32 v115, 0, v120
	v_mul_f32_e32 v120, v116, v116
	v_max_f32_e32 v116, 0, v121
	v_mul_f32_e32 v114, v114, v114
	v_mul_f32_e32 v115, v115, v115
	v_mul_f32_e32 v116, v116, v116
	v_mul_f32_e32 v118, v118, v118
	v_mul_f32_e32 v117, v117, v117
	v_cvt_pk_bf16_f32 v114, v118, v114
	v_cvt_pk_bf16_f32 v115, v115, v116
	v_cvt_pk_bf16_f32 v116, v122, v119
	v_cvt_pk_bf16_f32 v117, v120, v117
	v_lshl_add_u64 v[252:253], v[162:163], 0, s[58:59]
	global_store_dwordx4 v[252:253], v[114:117], off nt
	s_mov_b64 s[22:23], -1
	s_andn2_b64 vcc, exec, s[24:25]
	v_or_b32_e32 v116, 16, v146
	v_cndmask_b32_e64 v114, 0, 1, s[24:25]
	v_cmp_ne_u32_e64 s[4:5], 1, v114
	v_ashrrev_i32_e32 v117, 31, v116
	s_cbranch_vccnz .LBB0_1389
	v_lshlrev_b64 v[114:115], 6, v[116:117]
	v_lshl_add_u64 v[114:115], v[138:139], 0, v[114:115]
	global_load_dwordx4 v[118:121], v[114:115], off
	v_and_b32_e32 v115, 64, v159
	v_xor_b32_e32 v114, 16, v159
	v_add_u32_e32 v122, 64, v115
	v_cmp_lt_i32_e32 vcc, v114, v122
	s_mov_b64 s[22:23], 0
	s_waitcnt vmcnt(0)
	v_mov_b32_e32 v115, v120
	v_cndmask_b32_e32 v114, v159, v114, vcc
	v_lshlrev_b32_e32 v123, 2, v114
	v_mov_b32_e32 v114, v119
	v_mov_b32_e32 v119, v121
	v_pk_add_f32 v[114:115], v[114:115], v[118:119]
	v_xor_b32_e32 v118, 32, v159
	v_add_f32_e32 v114, v114, v115
	ds_bpermute_b32 v115, v123, v114
	v_cmp_lt_i32_e32 vcc, v118, v122
	s_waitcnt lgkmcnt(0)
	v_add_f32_e32 v114, v114, v115
	v_cndmask_b32_e32 v118, v159, v118, vcc
	v_lshlrev_b32_e32 v115, 2, v118
	ds_bpermute_b32 v115, v115, v114
	s_waitcnt lgkmcnt(0)
	v_add_f32_e32 v114, v114, v115
	v_fmamk_f32 v114, v114, 0x3a800000, v156
	v_rsq_f32_e32 v114, v114

; __device__ __forceinline__ unsigned cvt_pk_bf16(float lo, float hi) { unsigned r; asm volatile("v_cvt_pk_bf16_f32 %0, %1, %2" : "=v"(r) : "v"(lo), "v"(hi)); return r; }
;     __device__ __forceinline__ void operator()(const f32x4 (&acc)[2][2][4][2], const Unit& u, int wr, int wc, int fr, int fq) const {
;     ...
;             for (int m = 0; m < 4; ++m) { const int r = row0 + ai * HALF + m * 16;
;                 float rstd;
;                 if (u.idx < UP_TAB_ROUNDS) rstd = tab[u.idx * BM + ai * HALF + wr * 64 + m * 16 + fr];
;                 else { const f32x4 p = *(const f32x4*)(stats + (size_t)r * 16 + 4 * fq); float s = (p[0] + p[1]) + (p[2] + p[3]);
;                     s += __shfl_xor(s, 16); s += __shfl_xor(s, 32); rstd = __builtin_amdgcn_rsqf(s * (1.0f / 1024.0f) + RMS_EPS); }
;                 bf16_t* rowp = H + (size_t)r * 4096 + col0;
; #pragma unroll
;                 for (int bj = 0; bj < 2; ++bj) { f32x4 v0 = acc[ai][bj][m][0] * rstd, v1 = acc[ai][bj][m][1] * rstd;
; #pragma unroll
;                     for (int e = 0; e < 4; ++e) { const float a = fmaxf(v0[e], 0.f), b = fmaxf(v1[e], 0.f); v0[e] = a * a; v1[e] = b * b; }
;                     u32x4 w; w.x = cvt_pk_bf16(v0[0], v0[1]); w.y = cvt_pk_bf16(v0[2], v0[3]); w.z = cvt_pk_bf16(v1[0], v1[1]); w.w = cvt_pk_bf16(v1[2], v1[3]);
;                     __builtin_nontemporal_store(w, (u32x4*)(rowp + bj * HALF)); } }
.LBB0_1391:
	s_waitcnt lgkmcnt(0)
	v_pk_mul_f32 v[106:107], v[106:107], v[114:115] op_sel_hi:[1,0]
	v_pk_mul_f32 v[110:111], v[110:111], v[114:115] op_sel_hi:[1,0]
	v_pk_mul_f32 v[108:109], v[108:109], v[114:115] op_sel_hi:[1,0]
	v_max_f32_e32 v106, 0, v106
	v_lshlrev_b64 v[116:117], 7, v[116:117]
	v_pk_mul_f32 v[112:113], v[112:113], v[114:115] op_sel_hi:[1,0]
	v_mul_f32_e32 v115, v106, v106
	v_max_f32_e32 v106, 0, v111
	v_max_f32_e32 v107, 0, v107
	v_max_f32_e32 v108, 0, v108
	v_lshl_add_u64 v[116:117], s[56:57], 0, v[116:117]
	v_max_f32_e32 v110, 0, v110
	v_mul_f32_e32 v106, v106, v106
	v_mul_f32_e32 v111, v107, v107
	v_max_f32_e32 v107, 0, v112
	v_mul_f32_e32 v112, v108, v108
	v_max_f32_e32 v108, 0, v113
	v_max_f32_e32 v109, 0, v109
	v_pk_mul_f32 v[100:101], v[100:101], v[114:115] op_sel_hi:[1,0]
	v_pk_mul_f32 v[98:99], v[98:99], v[114:115] op_sel_hi:[1,0]
	v_lshl_add_u64 v[116:117], v[148:149], 1, v[116:117]
	v_mul_f32_e32 v110, v110, v110
	v_mul_f32_e32 v107, v107, v107
	v_mul_f32_e32 v108, v108, v108
	v_mul_f32_e32 v109, v109, v109
	v_cvt_pk_bf16_f32 v106, v110, v106
	v_pk_mul_f32 v[104:105], v[104:105], v[114:115] op_sel_hi:[1,0]
	v_pk_mul_f32 v[102:103], v[102:103], v[114:115] op_sel_hi:[1,0]
	v_max_f32_e32 v98, 0, v98
	v_max_f32_e32 v99, 0, v99
	v_max_f32_e32 v100, 0, v100
	v_cvt_pk_bf16_f32 v107, v107, v108
	v_cvt_pk_bf16_f32 v108, v115, v111
	v_cvt_pk_bf16_f32 v109, v112, v109
	global_store_dwordx4 v[116:117], v[106:109], off nt
	v_max_f32_e32 v102, 0, v102
	v_max_f32_e32 v101, 0, v101
	v_mul_f32_e32 v106, v98, v98
	v_max_f32_e32 v98, 0, v103
	v_mul_f32_e32 v103, v99, v99
	v_max_f32_e32 v99, 0, v104
	v_mul_f32_e32 v104, v100, v100
	v_max_f32_e32 v100, 0, v105
	v_mul_f32_e32 v98, v98, v98
	v_mul_f32_e32 v99, v99, v99
	v_mul_f32_e32 v100, v100, v100
	v_mul_f32_e32 v102, v102, v102
	v_mul_f32_e32 v101, v101, v101
	v_cvt_pk_bf16_f32 v98, v102, v98
	v_cvt_pk_bf16_f32 v99, v99, v100
	v_cvt_pk_bf16_f32 v100, v106, v103
	v_cvt_pk_bf16_f32 v101, v104, v101
	v_lshl_add_u64 v[252:253], v[116:117], 0, s[58:59]
	global_store_dwordx4 v[252:253], v[98:101], off nt
	s_mov_b64 s[22:23], -1
	s_and_b64 vcc, exec, s[4:5]
	v_or_b32_e32 v100, 32, v146
	v_ashrrev_i32_e32 v101, 31, v100
	s_cbranch_vccnz .LBB0_1393
	v_lshlrev_b64 v[98:99], 6, v[100:101]
	v_lshl_add_u64 v[98:99], v[138:139], 0, v[98:99]
	global_load_dwordx4 v[102:105], v[98:99], off
	v_and_b32_e32 v99, 64, v159
	v_xor_b32_e32 v98, 16, v159
	v_add_u32_e32 v106, 64, v99
	v_cmp_lt_i32_e32 vcc, v98, v106
	s_mov_b64 s[22:23], 0
	s_waitcnt vmcnt(0)
	v_mov_b32_e32 v99, v104
	v_cndmask_b32_e32 v98, v159, v98, vcc
	v_lshlrev_b32_e32 v107, 2, v98
	v_mov_b32_e32 v98, v103
	v_mov_b32_e32 v103, v105
	v_pk_add_f32 v[98:99], v[98:99], v[102:103]
	v_xor_b32_e32 v102, 32, v159
	v_add_f32_e32 v98, v98, v99
	ds_bpermute_b32 v99, v107, v98
	v_cmp_lt_i32_e32 vcc, v102, v106
	s_waitcnt lgkmcnt(0)
	v_add_f32_e32 v98, v98, v99
	v_cndmask_b32_e32 v102, v159, v102, vcc
	v_lshlrev_b32_e32 v99, 2, v102
	ds_bpermute_b32 v99, v99, v98
	s_waitcnt lgkmcnt(0)
	v_add_f32_e32 v98, v98, v99
	v_fmamk_f32 v98, v98, 0x3a800000, v156
	v_rsq_f32_e32 v98, v98

; __device__ __forceinline__ unsigned cvt_pk_bf16(float lo, float hi) { unsigned r; asm volatile("v_cvt_pk_bf16_f32 %0, %1, %2" : "=v"(r) : "v"(lo), "v"(hi)); return r; }
;     __device__ __forceinline__ void operator()(const f32x4 (&acc)[2][2][4][2], const Unit& u, int wr, int wc, int fr, int fq) const {
;     ...
;             for (int m = 0; m < 4; ++m) { const int r = row0 + ai * HALF + m * 16;
;                 float rstd;
;                 if (u.idx < UP_TAB_ROUNDS) rstd = tab[u.idx * BM + ai * HALF + wr * 64 + m * 16 + fr];
;                 else { const f32x4 p = *(const f32x4*)(stats + (size_t)r * 16 + 4 * fq); float s = (p[0] + p[1]) + (p[2] + p[3]);
;                     s += __shfl_xor(s, 16); s += __shfl_xor(s, 32); rstd = __builtin_amdgcn_rsqf(s * (1.0f / 1024.0f) + RMS_EPS); }
;                 bf16_t* rowp = H + (size_t)r * 4096 + col0;
; #pragma unroll
;                 for (int bj = 0; bj < 2; ++bj) { f32x4 v0 = acc[ai][bj][m][0] * rstd, v1 = acc[ai][bj][m][1] * rstd;
; #pragma unroll
;                     for (int e = 0; e < 4; ++e) { const float a = fmaxf(v0[e], 0.f), b = fmaxf(v1[e], 0.f); v0[e] = a * a; v1[e] = b * b; }
;                     u32x4 w; w.x = cvt_pk_bf16(v0[0], v0[1]); w.y = cvt_pk_bf16(v0[2], v0[3]); w.z = cvt_pk_bf16(v1[0], v1[1]); w.w = cvt_pk_bf16(v1[2], v1[3]);
;                     __builtin_nontemporal_store(w, (u32x4*)(rowp + bj * HALF)); } }
.LBB0_1395:
	s_waitcnt lgkmcnt(0)
	v_pk_mul_f32 v[90:91], v[90:91], v[98:99] op_sel_hi:[1,0]
	v_pk_mul_f32 v[94:95], v[94:95], v[98:99] op_sel_hi:[1,0]
	v_pk_mul_f32 v[92:93], v[92:93], v[98:99] op_sel_hi:[1,0]
	v_max_f32_e32 v90, 0, v90
	v_lshlrev_b64 v[100:101], 7, v[100:101]
	v_pk_mul_f32 v[96:97], v[96:97], v[98:99] op_sel_hi:[1,0]
	v_mul_f32_e32 v99, v90, v90
	v_max_f32_e32 v90, 0, v95
	v_max_f32_e32 v91, 0, v91
	v_max_f32_e32 v92, 0, v92
	v_lshl_add_u64 v[100:101], s[56:57], 0, v[100:101]
	v_max_f32_e32 v94, 0, v94
	v_mul_f32_e32 v90, v90, v90
	v_mul_f32_e32 v95, v91, v91
	v_max_f32_e32 v91, 0, v96
	v_mul_f32_e32 v96, v92, v92
	v_max_f32_e32 v92, 0, v97
	v_max_f32_e32 v93, 0, v93
	v_pk_mul_f32 v[84:85], v[84:85], v[98:99] op_sel_hi:[1,0]
	v_pk_mul_f32 v[82:83], v[82:83], v[98:99] op_sel_hi:[1,0]
	v_lshl_add_u64 v[100:101], v[148:149], 1, v[100:101]
	v_mul_f32_e32 v94, v94, v94
	v_mul_f32_e32 v91, v91, v91
	v_mul_f32_e32 v92, v92, v92
	v_mul_f32_e32 v93, v93, v93
	v_cvt_pk_bf16_f32 v90, v94, v90
	v_pk_mul_f32 v[88:89], v[88:89], v[98:99] op_sel_hi:[1,0]
	v_pk_mul_f32 v[86:87], v[86:87], v[98:99] op_sel_hi:[1,0]
	v_max_f32_e32 v82, 0, v82
	v_max_f32_e32 v83, 0, v83
	v_max_f32_e32 v84, 0, v84
	v_cvt_pk_bf16_f32 v91, v91, v92
	v_cvt_pk_bf16_f32 v92, v99, v95
	v_cvt_pk_bf16_f32 v93, v96, v93
	global_store_dwordx4 v[100:101], v[90:93], off nt
	v_max_f32_e32 v86, 0, v86
	v_max_f32_e32 v85, 0, v85
	v_mul_f32_e32 v90, v82, v82
	v_max_f32_e32 v82, 0, v87
	v_mul_f32_e32 v87, v83, v83
	v_max_f32_e32 v83, 0, v88
	v_mul_f32_e32 v88, v84, v84
	v_max_f32_e32 v84, 0, v89
	v_mul_f32_e32 v82, v82, v82
	v_mul_f32_e32 v83, v83, v83
	v_mul_f32_e32 v84, v84, v84
	v_mul_f32_e32 v86, v86, v86
	v_mul_f32_e32 v85, v85, v85
	v_cvt_pk_bf16_f32 v82, v86, v82
	v_cvt_pk_bf16_f32 v83, v83, v84
	v_cvt_pk_bf16_f32 v84, v90, v87
	v_cvt_pk_bf16_f32 v85, v88, v85
	v_lshl_add_u64 v[252:253], v[100:101], 0, s[58:59]
	global_store_dwordx4 v[252:253], v[82:85], off nt
	s_mov_b64 s[22:23], -1
	s_and_b64 vcc, exec, s[4:5]
	v_or_b32_e32 v84, 48, v146
	v_ashrrev_i32_e32 v85, 31, v84
	s_cbranch_vccnz .LBB0_1397
	v_lshlrev_b64 v[82:83], 6, v[84:85]
	v_lshl_add_u64 v[82:83], v[138:139], 0, v[82:83]
	global_load_dwordx4 v[86:89], v[82:83], off
	v_and_b32_e32 v83, 64, v159
	v_xor_b32_e32 v82, 16, v159
	v_add_u32_e32 v90, 64, v83
	v_cmp_lt_i32_e32 vcc, v82, v90
	s_mov_b64 s[22:23], 0
	s_waitcnt vmcnt(0)
	v_mov_b32_e32 v83, v88
	v_cndmask_b32_e32 v82, v159, v82, vcc
	v_lshlrev_b32_e32 v91, 2, v82
	v_mov_b32_e32 v82, v87
	v_mov_b32_e32 v87, v89
	v_pk_add_f32 v[82:83], v[82:83], v[86:87]
	v_xor_b32_e32 v86, 32, v159
	v_add_f32_e32 v82, v82, v83
	ds_bpermute_b32 v83, v91, v82
	v_cmp_lt_i32_e32 vcc, v86, v90
	s_waitcnt lgkmcnt(0)
	v_add_f32_e32 v82, v82, v83
	v_cndmask_b32_e32 v86, v159, v86, vcc
	v_lshlrev_b32_e32 v83, 2, v86
	ds_bpermute_b32 v83, v83, v82
	s_waitcnt lgkmcnt(0)
	v_add_f32_e32 v82, v82, v83
	v_fmamk_f32 v82, v82, 0x3a800000, v156
	v_rsq_f32_e32 v82, v82

; __device__ __forceinline__ unsigned cvt_pk_bf16(float lo, float hi) { unsigned r; asm volatile("v_cvt_pk_bf16_f32 %0, %1, %2" : "=v"(r) : "v"(lo), "v"(hi)); return r; }
;     __device__ __forceinline__ void operator()(const f32x4 (&acc)[2][2][4][2], const Unit& u, int wr, int wc, int fr, int fq) const {
;     ...
;             for (int m = 0; m < 4; ++m) { const int r = row0 + ai * HALF + m * 16;
;                 float rstd;
;                 if (u.idx < UP_TAB_ROUNDS) rstd = tab[u.idx * BM + ai * HALF + wr * 64 + m * 16 + fr];
;                 else { const f32x4 p = *(const f32x4*)(stats + (size_t)r * 16 + 4 * fq); float s = (p[0] + p[1]) + (p[2] + p[3]);
;                     s += __shfl_xor(s, 16); s += __shfl_xor(s, 32); rstd = __builtin_amdgcn_rsqf(s * (1.0f / 1024.0f) + RMS_EPS); }
;                 bf16_t* rowp = H + (size_t)r * 4096 + col0;
; #pragma unroll
;                 for (int bj = 0; bj < 2; ++bj) { f32x4 v0 = acc[ai][bj][m][0] * rstd, v1 = acc[ai][bj][m][1] * rstd;
; #pragma unroll
;                     for (int e = 0; e < 4; ++e) { const float a = fmaxf(v0[e], 0.f), b = fmaxf(v1[e], 0.f); v0[e] = a * a; v1[e] = b * b; }
;                     u32x4 w; w.x = cvt_pk_bf16(v0[0], v0[1]); w.y = cvt_pk_bf16(v0[2], v0[3]); w.z = cvt_pk_bf16(v1[0], v1[1]); w.w = cvt_pk_bf16(v1[2], v1[3]);
;                     __builtin_nontemporal_store(w, (u32x4*)(rowp + bj * HALF)); } }
.LBB0_1399:
	s_waitcnt lgkmcnt(0)
	v_pk_mul_f32 v[74:75], v[74:75], v[82:83] op_sel_hi:[1,0]
	v_pk_mul_f32 v[78:79], v[78:79], v[82:83] op_sel_hi:[1,0]
	v_pk_mul_f32 v[76:77], v[76:77], v[82:83] op_sel_hi:[1,0]
	v_max_f32_e32 v74, 0, v74
	v_lshlrev_b64 v[84:85], 7, v[84:85]
	v_pk_mul_f32 v[80:81], v[80:81], v[82:83] op_sel_hi:[1,0]
	v_mul_f32_e32 v83, v74, v74
	v_max_f32_e32 v74, 0, v79
	v_max_f32_e32 v75, 0, v75
	v_max_f32_e32 v76, 0, v76
	v_lshl_add_u64 v[84:85], s[56:57], 0, v[84:85]
	v_max_f32_e32 v78, 0, v78
	v_mul_f32_e32 v74, v74, v74
	v_mul_f32_e32 v79, v75, v75
	v_max_f32_e32 v75, 0, v80
	v_mul_f32_e32 v80, v76, v76
	v_max_f32_e32 v76, 0, v81
	v_max_f32_e32 v77, 0, v77
	v_pk_mul_f32 v[68:69], v[68:69], v[82:83] op_sel_hi:[1,0]
	v_pk_mul_f32 v[66:67], v[66:67], v[82:83] op_sel_hi:[1,0]
	v_lshl_add_u64 v[84:85], v[148:149], 1, v[84:85]
	v_mul_f32_e32 v78, v78, v78
	v_mul_f32_e32 v75, v75, v75
	v_mul_f32_e32 v76, v76, v76
	v_mul_f32_e32 v77, v77, v77
	v_cvt_pk_bf16_f32 v74, v78, v74
	v_pk_mul_f32 v[72:73], v[72:73], v[82:83] op_sel_hi:[1,0]
	v_pk_mul_f32 v[70:71], v[70:71], v[82:83] op_sel_hi:[1,0]
	v_max_f32_e32 v66, 0, v66
	v_max_f32_e32 v67, 0, v67
	v_max_f32_e32 v68, 0, v68
	v_cvt_pk_bf16_f32 v75, v75, v76
	v_cvt_pk_bf16_f32 v76, v83, v79
	v_cvt_pk_bf16_f32 v77, v80, v77
	global_store_dwordx4 v[84:85], v[74:77], off nt
	v_max_f32_e32 v70, 0, v70
	v_max_f32_e32 v69, 0, v69
	v_mul_f32_e32 v74, v66, v66
	v_max_f32_e32 v66, 0, v71
	v_mul_f32_e32 v71, v67, v67
	v_max_f32_e32 v67, 0, v72
	v_mul_f32_e32 v72, v68, v68
	v_max_f32_e32 v68, 0, v73
	v_mul_f32_e32 v66, v66, v66
	v_mul_f32_e32 v67, v67, v67
	v_mul_f32_e32 v68, v68, v68
	v_mul_f32_e32 v70, v70, v70
	v_mul_f32_e32 v69, v69, v69
	v_cvt_pk_bf16_f32 v66, v70, v66
	v_cvt_pk_bf16_f32 v67, v67, v68
	v_cvt_pk_bf16_f32 v68, v74, v71
	v_cvt_pk_bf16_f32 v69, v72, v69
	v_lshl_add_u64 v[252:253], v[84:85], 0, s[58:59]
	global_store_dwordx4 v[252:253], v[66:69], off nt
	s_mov_b64 s[22:23], -1
	s_and_b64 vcc, exec, s[4:5]
	v_add_u32_e32 v68, 0x80, v146
	v_ashrrev_i32_e32 v69, 31, v68
	s_cbranch_vccnz .LBB0_1401
	v_lshlrev_b64 v[66:67], 6, v[68:69]
	v_lshl_add_u64 v[66:67], v[138:139], 0, v[66:67]
	global_load_dwordx4 v[70:73], v[66:67], off
	v_and_b32_e32 v67, 64, v159
	v_xor_b32_e32 v66, 16, v159
	v_add_u32_e32 v74, 64, v67
	v_cmp_lt_i32_e32 vcc, v66, v74
	s_mov_b64 s[22:23], 0
	s_waitcnt vmcnt(0)
	v_mov_b32_e32 v67, v72
	v_cndmask_b32_e32 v66, v159, v66, vcc
	v_lshlrev_b32_e32 v75, 2, v66
	v_mov_b32_e32 v66, v71
	v_mov_b32_e32 v71, v73
	v_pk_add_f32 v[66:67], v[66:67], v[70:71]
	v_xor_b32_e32 v70, 32, v159
	v_add_f32_e32 v66, v66, v67
	ds_bpermute_b32 v67, v75, v66
	v_cmp_lt_i32_e32 vcc, v70, v74
	s_waitcnt lgkmcnt(0)
	v_add_f32_e32 v66, v66, v67
	v_cndmask_b32_e32 v70, v159, v70, vcc
	v_lshlrev_b32_e32 v67, 2, v70
	ds_bpermute_b32 v67, v67, v66
	s_waitcnt lgkmcnt(0)
	v_add_f32_e32 v66, v66, v67
	v_fmamk_f32 v66, v66, 0x3a800000, v156
	v_rsq_f32_e32 v66, v66

; __device__ __forceinline__ unsigned cvt_pk_bf16(float lo, float hi) { unsigned r; asm volatile("v_cvt_pk_bf16_f32 %0, %1, %2" : "=v"(r) : "v"(lo), "v"(hi)); return r; }
;     __device__ __forceinline__ void operator()(const f32x4 (&acc)[2][2][4][2], const Unit& u, int wr, int wc, int fr, int fq) const {
;     ...
;             for (int m = 0; m < 4; ++m) { const int r = row0 + ai * HALF + m * 16;
;                 float rstd;
;                 if (u.idx < UP_TAB_ROUNDS) rstd = tab[u.idx * BM + ai * HALF + wr * 64 + m * 16 + fr];
;                 else { const f32x4 p = *(const f32x4*)(stats + (size_t)r * 16 + 4 * fq); float s = (p[0] + p[1]) + (p[2] + p[3]);
;                     s += __shfl_xor(s, 16); s += __shfl_xor(s, 32); rstd = __builtin_amdgcn_rsqf(s * (1.0f / 1024.0f) + RMS_EPS); }
;                 bf16_t* rowp = H + (size_t)r * 4096 + col0;
; #pragma unroll
;                 for (int bj = 0; bj < 2; ++bj) { f32x4 v0 = acc[ai][bj][m][0] * rstd, v1 = acc[ai][bj][m][1] * rstd;
; #pragma unroll
;                     for (int e = 0; e < 4; ++e) { const float a = fmaxf(v0[e], 0.f), b = fmaxf(v1[e], 0.f); v0[e] = a * a; v1[e] = b * b; }
;                     u32x4 w; w.x = cvt_pk_bf16(v0[0], v0[1]); w.y = cvt_pk_bf16(v0[2], v0[3]); w.z = cvt_pk_bf16(v1[0], v1[1]); w.w = cvt_pk_bf16(v1[2], v1[3]);
;                     __builtin_nontemporal_store(w, (u32x4*)(rowp + bj * HALF)); } }
.LBB0_1403:
	s_waitcnt lgkmcnt(0)
	v_pk_mul_f32 v[58:59], v[58:59], v[66:67] op_sel_hi:[1,0]
	v_pk_mul_f32 v[62:63], v[62:63], v[66:67] op_sel_hi:[1,0]
	v_pk_mul_f32 v[60:61], v[60:61], v[66:67] op_sel_hi:[1,0]
	v_max_f32_e32 v58, 0, v58
	v_lshlrev_b64 v[68:69], 7, v[68:69]
	v_pk_mul_f32 v[64:65], v[64:65], v[66:67] op_sel_hi:[1,0]
	v_mul_f32_e32 v67, v58, v58
	v_max_f32_e32 v58, 0, v63
	v_max_f32_e32 v59, 0, v59
	v_max_f32_e32 v60, 0, v60
	v_lshl_add_u64 v[68:69], s[56:57], 0, v[68:69]
	v_max_f32_e32 v62, 0, v62
	v_mul_f32_e32 v58, v58, v58
	v_mul_f32_e32 v63, v59, v59
	v_max_f32_e32 v59, 0, v64
	v_mul_f32_e32 v64, v60, v60
	v_max_f32_e32 v60, 0, v65
	v_max_f32_e32 v61, 0, v61
	v_pk_mul_f32 v[52:53], v[52:53], v[66:67] op_sel_hi:[1,0]
	v_pk_mul_f32 v[50:51], v[50:51], v[66:67] op_sel_hi:[1,0]
	v_lshl_add_u64 v[68:69], v[148:149], 1, v[68:69]
	v_mul_f32_e32 v62, v62, v62
	v_mul_f32_e32 v59, v59, v59
	v_mul_f32_e32 v60, v60, v60
	v_mul_f32_e32 v61, v61, v61
	v_cvt_pk_bf16_f32 v58, v62, v58
	v_pk_mul_f32 v[56:57], v[56:57], v[66:67] op_sel_hi:[1,0]
	v_pk_mul_f32 v[54:55], v[54:55], v[66:67] op_sel_hi:[1,0]
	v_max_f32_e32 v50, 0, v50
	v_max_f32_e32 v51, 0, v51
	v_max_f32_e32 v52, 0, v52
	v_cvt_pk_bf16_f32 v59, v59, v60
	v_cvt_pk_bf16_f32 v60, v67, v63
	v_cvt_pk_bf16_f32 v61, v64, v61
	global_store_dwordx4 v[68:69], v[58:61], off nt
	v_max_f32_e32 v54, 0, v54
	v_max_f32_e32 v53, 0, v53
	v_mul_f32_e32 v58, v50, v50
	v_max_f32_e32 v50, 0, v55
	v_mul_f32_e32 v55, v51, v51
	v_max_f32_e32 v51, 0, v56
	v_mul_f32_e32 v56, v52, v52
	v_max_f32_e32 v52, 0, v57
	v_mul_f32_e32 v50, v50, v50
	v_mul_f32_e32 v51, v51, v51
	v_mul_f32_e32 v52, v52, v52
	v_mul_f32_e32 v54, v54, v54
	v_mul_f32_e32 v53, v53, v53
	v_cvt_pk_bf16_f32 v50, v54, v50
	v_cvt_pk_bf16_f32 v51, v51, v52
	v_cvt_pk_bf16_f32 v52, v58, v55
	v_cvt_pk_bf16_f32 v53, v56, v53
	v_lshl_add_u64 v[252:253], v[68:69], 0, s[58:59]
	global_store_dwordx4 v[252:253], v[50:53], off nt
	s_mov_b64 s[22:23], -1
	s_and_b64 vcc, exec, s[4:5]
	v_add_u32_e32 v52, 0x90, v146
	v_ashrrev_i32_e32 v53, 31, v52
	s_cbranch_vccnz .LBB0_1405
	v_lshlrev_b64 v[50:51], 6, v[52:53]
	v_lshl_add_u64 v[50:51], v[138:139], 0, v[50:51]
	global_load_dwordx4 v[54:57], v[50:51], off
	v_and_b32_e32 v51, 64, v159
	v_xor_b32_e32 v50, 16, v159
	v_add_u32_e32 v58, 64, v51
	v_cmp_lt_i32_e32 vcc, v50, v58
	s_mov_b64 s[22:23], 0
	s_waitcnt vmcnt(0)
	v_mov_b32_e32 v51, v56
	v_cndmask_b32_e32 v50, v159, v50, vcc
	v_lshlrev_b32_e32 v59, 2, v50
	v_mov_b32_e32 v50, v55
	v_mov_b32_e32 v55, v57
	v_pk_add_f32 v[50:51], v[50:51], v[54:55]
	v_xor_b32_e32 v54, 32, v159
	v_add_f32_e32 v50, v50, v51
	ds_bpermute_b32 v51, v59, v50
	v_cmp_lt_i32_e32 vcc, v54, v58
	s_waitcnt lgkmcnt(0)
	v_add_f32_e32 v50, v50, v51
	v_cndmask_b32_e32 v54, v159, v54, vcc
	v_lshlrev_b32_e32 v51, 2, v54
	ds_bpermute_b32 v51, v51, v50
	s_waitcnt lgkmcnt(0)
	v_add_f32_e32 v50, v50, v51
	v_fmamk_f32 v50, v50, 0x3a800000, v156
	v_rsq_f32_e32 v50, v50

; __device__ __forceinline__ unsigned cvt_pk_bf16(float lo, float hi) { unsigned r; asm volatile("v_cvt_pk_bf16_f32 %0, %1, %2" : "=v"(r) : "v"(lo), "v"(hi)); return r; }
;     __device__ __forceinline__ void operator()(const f32x4 (&acc)[2][2][4][2], const Unit& u, int wr, int wc, int fr, int fq) const {
;     ...
;             for (int m = 0; m < 4; ++m) { const int r = row0 + ai * HALF + m * 16;
;                 float rstd;
;                 if (u.idx < UP_TAB_ROUNDS) rstd = tab[u.idx * BM + ai * HALF + wr * 64 + m * 16 + fr];
;                 else { const f32x4 p = *(const f32x4*)(stats + (size_t)r * 16 + 4 * fq); float s = (p[0] + p[1]) + (p[2] + p[3]);
;                     s += __shfl_xor(s, 16); s += __shfl_xor(s, 32); rstd = __builtin_amdgcn_rsqf(s * (1.0f / 1024.0f) + RMS_EPS); }
;                 bf16_t* rowp = H + (size_t)r * 4096 + col0;
; #pragma unroll
;                 for (int bj = 0; bj < 2; ++bj) { f32x4 v0 = acc[ai][bj][m][0] * rstd, v1 = acc[ai][bj][m][1] * rstd;
; #pragma unroll
;                     for (int e = 0; e < 4; ++e) { const float a = fmaxf(v0[e], 0.f), b = fmaxf(v1[e], 0.f); v0[e] = a * a; v1[e] = b * b; }
;                     u32x4 w; w.x = cvt_pk_bf16(v0[0], v0[1]); w.y = cvt_pk_bf16(v0[2], v0[3]); w.z = cvt_pk_bf16(v1[0], v1[1]); w.w = cvt_pk_bf16(v1[2], v1[3]);
;                     __builtin_nontemporal_store(w, (u32x4*)(rowp + bj * HALF)); } }
.LBB0_1407:
	s_waitcnt lgkmcnt(0)
	v_pk_mul_f32 v[42:43], v[42:43], v[50:51] op_sel_hi:[1,0]
	v_pk_mul_f32 v[46:47], v[46:47], v[50:51] op_sel_hi:[1,0]
	v_pk_mul_f32 v[44:45], v[44:45], v[50:51] op_sel_hi:[1,0]
	v_max_f32_e32 v42, 0, v42
	v_lshlrev_b64 v[52:53], 7, v[52:53]
	v_pk_mul_f32 v[48:49], v[48:49], v[50:51] op_sel_hi:[1,0]
	v_mul_f32_e32 v51, v42, v42
	v_max_f32_e32 v42, 0, v47
	v_max_f32_e32 v43, 0, v43
	v_max_f32_e32 v44, 0, v44
	v_lshl_add_u64 v[52:53], s[56:57], 0, v[52:53]
	v_max_f32_e32 v46, 0, v46
	v_mul_f32_e32 v42, v42, v42
	v_mul_f32_e32 v47, v43, v43
	v_max_f32_e32 v43, 0, v48
	v_mul_f32_e32 v48, v44, v44
	v_max_f32_e32 v44, 0, v49
	v_max_f32_e32 v45, 0, v45
	v_pk_mul_f32 v[36:37], v[36:37], v[50:51] op_sel_hi:[1,0]
	v_pk_mul_f32 v[34:35], v[34:35], v[50:51] op_sel_hi:[1,0]
	v_lshl_add_u64 v[52:53], v[148:149], 1, v[52:53]
	v_mul_f32_e32 v46, v46, v46
	v_mul_f32_e32 v43, v43, v43
	v_mul_f32_e32 v44, v44, v44
	v_mul_f32_e32 v45, v45, v45
	v_cvt_pk_bf16_f32 v42, v46, v42
	v_pk_mul_f32 v[40:41], v[40:41], v[50:51] op_sel_hi:[1,0]
	v_pk_mul_f32 v[38:39], v[38:39], v[50:51] op_sel_hi:[1,0]
	v_max_f32_e32 v34, 0, v34
	v_max_f32_e32 v35, 0, v35
	v_max_f32_e32 v36, 0, v36
	v_cvt_pk_bf16_f32 v43, v43, v44
	v_cvt_pk_bf16_f32 v44, v51, v47
	v_cvt_pk_bf16_f32 v45, v48, v45
	global_store_dwordx4 v[52:53], v[42:45], off nt
	v_max_f32_e32 v38, 0, v38
	v_max_f32_e32 v37, 0, v37
	v_mul_f32_e32 v42, v34, v34
	v_max_f32_e32 v34, 0, v39
	v_mul_f32_e32 v39, v35, v35
	v_max_f32_e32 v35, 0, v40
	v_mul_f32_e32 v40, v36, v36
	v_max_f32_e32 v36, 0, v41
	v_mul_f32_e32 v34, v34, v34
	v_mul_f32_e32 v35, v35, v35
	v_mul_f32_e32 v36, v36, v36
	v_mul_f32_e32 v38, v38, v38
	v_mul_f32_e32 v37, v37, v37
	v_cvt_pk_bf16_f32 v34, v38, v34
	v_cvt_pk_bf16_f32 v35, v35, v36
	v_cvt_pk_bf16_f32 v36, v42, v39
	v_cvt_pk_bf16_f32 v37, v40, v37
	v_lshl_add_u64 v[252:253], v[52:53], 0, s[58:59]
	global_store_dwordx4 v[252:253], v[34:37], off nt
	s_mov_b64 s[22:23], -1
	s_and_b64 vcc, exec, s[4:5]
	v_add_u32_e32 v36, 0xa0, v146
	v_ashrrev_i32_e32 v37, 31, v36
	s_cbranch_vccnz .LBB0_1409
	v_lshlrev_b64 v[34:35], 6, v[36:37]
	v_lshl_add_u64 v[34:35], v[138:139], 0, v[34:35]
	global_load_dwordx4 v[38:41], v[34:35], off
	v_and_b32_e32 v35, 64, v159
	v_xor_b32_e32 v34, 16, v159
	v_add_u32_e32 v42, 64, v35
	v_cmp_lt_i32_e32 vcc, v34, v42
	s_mov_b64 s[22:23], 0
	s_waitcnt vmcnt(0)
	v_mov_b32_e32 v35, v40
	v_cndmask_b32_e32 v34, v159, v34, vcc
	v_lshlrev_b32_e32 v43, 2, v34
	v_mov_b32_e32 v34, v39
	v_mov_b32_e32 v39, v41
	v_pk_add_f32 v[34:35], v[34:35], v[38:39]
	v_xor_b32_e32 v38, 32, v159
	v_add_f32_e32 v34, v34, v35
	ds_bpermute_b32 v35, v43, v34
	v_cmp_lt_i32_e32 vcc, v38, v42
	s_waitcnt lgkmcnt(0)
	v_add_f32_e32 v34, v34, v35
	v_cndmask_b32_e32 v38, v159, v38, vcc
	v_lshlrev_b32_e32 v35, 2, v38
	ds_bpermute_b32 v35, v35, v34
	s_waitcnt lgkmcnt(0)
	v_add_f32_e32 v34, v34, v35
	v_fmamk_f32 v34, v34, 0x3a800000, v156
	v_rsq_f32_e32 v34, v34

; __device__ __forceinline__ unsigned cvt_pk_bf16(float lo, float hi) { unsigned r; asm volatile("v_cvt_pk_bf16_f32 %0, %1, %2" : "=v"(r) : "v"(lo), "v"(hi)); return r; }
;     __device__ __forceinline__ void operator()(const f32x4 (&acc)[2][2][4][2], const Unit& u, int wr, int wc, int fr, int fq) const {
;     ...
;             for (int m = 0; m < 4; ++m) { const int r = row0 + ai * HALF + m * 16;
;                 float rstd;
;                 if (u.idx < UP_TAB_ROUNDS) rstd = tab[u.idx * BM + ai * HALF + wr * 64 + m * 16 + fr];
;                 else { const f32x4 p = *(const f32x4*)(stats + (size_t)r * 16 + 4 * fq); float s = (p[0] + p[1]) + (p[2] + p[3]);
;                     s += __shfl_xor(s, 16); s += __shfl_xor(s, 32); rstd = __builtin_amdgcn_rsqf(s * (1.0f / 1024.0f) + RMS_EPS); }
;                 bf16_t* rowp = H + (size_t)r * 4096 + col0;
; #pragma unroll
;                 for (int bj = 0; bj < 2; ++bj) { f32x4 v0 = acc[ai][bj][m][0] * rstd, v1 = acc[ai][bj][m][1] * rstd;
; #pragma unroll
;                     for (int e = 0; e < 4; ++e) { const float a = fmaxf(v0[e], 0.f), b = fmaxf(v1[e], 0.f); v0[e] = a * a; v1[e] = b * b; }
;                     u32x4 w; w.x = cvt_pk_bf16(v0[0], v0[1]); w.y = cvt_pk_bf16(v0[2], v0[3]); w.z = cvt_pk_bf16(v1[0], v1[1]); w.w = cvt_pk_bf16(v1[2], v1[3]);
;                     __builtin_nontemporal_store(w, (u32x4*)(rowp + bj * HALF)); } }
.LBB0_1411:
	s_waitcnt lgkmcnt(0)
	v_pk_mul_f32 v[26:27], v[26:27], v[34:35] op_sel_hi:[1,0]
	v_pk_mul_f32 v[30:31], v[30:31], v[34:35] op_sel_hi:[1,0]
	v_pk_mul_f32 v[28:29], v[28:29], v[34:35] op_sel_hi:[1,0]
	v_max_f32_e32 v26, 0, v26
	v_lshlrev_b64 v[36:37], 7, v[36:37]
	v_pk_mul_f32 v[32:33], v[32:33], v[34:35] op_sel_hi:[1,0]
	v_mul_f32_e32 v35, v26, v26
	v_max_f32_e32 v26, 0, v31
	v_max_f32_e32 v27, 0, v27
	v_max_f32_e32 v28, 0, v28
	v_lshl_add_u64 v[36:37], s[56:57], 0, v[36:37]
	v_max_f32_e32 v30, 0, v30
	v_mul_f32_e32 v26, v26, v26
	v_mul_f32_e32 v31, v27, v27
	v_max_f32_e32 v27, 0, v32
	v_mul_f32_e32 v32, v28, v28
	v_max_f32_e32 v28, 0, v33
	v_max_f32_e32 v29, 0, v29
	v_pk_mul_f32 v[20:21], v[20:21], v[34:35] op_sel_hi:[1,0]
	v_pk_mul_f32 v[18:19], v[18:19], v[34:35] op_sel_hi:[1,0]
	v_lshl_add_u64 v[36:37], v[148:149], 1, v[36:37]
	v_mul_f32_e32 v30, v30, v30
	v_mul_f32_e32 v27, v27, v27
	v_mul_f32_e32 v28, v28, v28
	v_mul_f32_e32 v29, v29, v29
	v_cvt_pk_bf16_f32 v26, v30, v26
	v_pk_mul_f32 v[24:25], v[24:25], v[34:35] op_sel_hi:[1,0]
	v_pk_mul_f32 v[22:23], v[22:23], v[34:35] op_sel_hi:[1,0]
	v_max_f32_e32 v18, 0, v18
	v_max_f32_e32 v19, 0, v19
	v_max_f32_e32 v20, 0, v20
	v_cvt_pk_bf16_f32 v27, v27, v28
	v_cvt_pk_bf16_f32 v28, v35, v31
	v_cvt_pk_bf16_f32 v29, v32, v29
	global_store_dwordx4 v[36:37], v[26:29], off nt
	v_max_f32_e32 v22, 0, v22
	v_max_f32_e32 v21, 0, v21
	v_mul_f32_e32 v26, v18, v18
	v_max_f32_e32 v18, 0, v23
	v_mul_f32_e32 v23, v19, v19
	v_max_f32_e32 v19, 0, v24
	v_mul_f32_e32 v24, v20, v20
	v_max_f32_e32 v20, 0, v25
	v_mul_f32_e32 v18, v18, v18
	v_mul_f32_e32 v19, v19, v19
	v_mul_f32_e32 v20, v20, v20
	v_mul_f32_e32 v22, v22, v22
	v_mul_f32_e32 v21, v21, v21
	v_cvt_pk_bf16_f32 v18, v22, v18
	v_cvt_pk_bf16_f32 v19, v19, v20
	v_cvt_pk_bf16_f32 v20, v26, v23
	v_cvt_pk_bf16_f32 v21, v24, v21
	v_lshl_add_u64 v[252:253], v[36:37], 0, s[58:59]
	global_store_dwordx4 v[252:253], v[18:21], off nt
	s_mov_b64 s[22:23], -1
	s_and_b64 vcc, exec, s[4:5]
	v_add_u32_e32 v20, 0xb0, v146
	v_ashrrev_i32_e32 v21, 31, v20
	s_cbranch_vccnz .LBB0_1413
	v_lshlrev_b64 v[18:19], 6, v[20:21]
	v_lshl_add_u64 v[18:19], v[138:139], 0, v[18:19]
	global_load_dwordx4 v[22:25], v[18:19], off
	v_and_b32_e32 v19, 64, v159
	v_xor_b32_e32 v18, 16, v159
	v_add_u32_e32 v26, 64, v19
	v_cmp_lt_i32_e32 vcc, v18, v26
	s_mov_b64 s[22:23], 0
	s_waitcnt vmcnt(0)
	v_mov_b32_e32 v19, v24
	v_cndmask_b32_e32 v18, v159, v18, vcc
	v_lshlrev_b32_e32 v27, 2, v18
	v_mov_b32_e32 v18, v23
	v_mov_b32_e32 v23, v25
	v_pk_add_f32 v[18:19], v[18:19], v[22:23]
	v_xor_b32_e32 v22, 32, v159
	v_add_f32_e32 v18, v18, v19
	ds_bpermute_b32 v19, v27, v18
	v_cmp_lt_i32_e32 vcc, v22, v26
	s_waitcnt lgkmcnt(0)
	v_add_f32_e32 v18, v18, v19
	v_cndmask_b32_e32 v22, v159, v22, vcc
	v_lshlrev_b32_e32 v19, 2, v22
	ds_bpermute_b32 v19, v19, v18
	s_waitcnt lgkmcnt(0)
	v_add_f32_e32 v18, v18, v19
	v_fmamk_f32 v18, v18, 0x3a800000, v156
	v_rsq_f32_e32 v18, v18

; __device__ __forceinline__ unsigned cvt_pk_bf16(float lo, float hi) { unsigned r; asm volatile("v_cvt_pk_bf16_f32 %0, %1, %2" : "=v"(r) : "v"(lo), "v"(hi)); return r; }
;     __device__ __forceinline__ void operator()(const f32x4 (&acc)[2][2][4][2], const Unit& u, int wr, int wc, int fr, int fq) const {
;     ...
;                 for (int bj = 0; bj < 2; ++bj) { f32x4 v0 = acc[ai][bj][m][0] * rstd, v1 = acc[ai][bj][m][1] * rstd;
; #pragma unroll
;                     for (int e = 0; e < 4; ++e) { const float a = fmaxf(v0[e], 0.f), b = fmaxf(v1[e], 0.f); v0[e] = a * a; v1[e] = b * b; }
;                     u32x4 w; w.x = cvt_pk_bf16(v0[0], v0[1]); w.y = cvt_pk_bf16(v0[2], v0[3]); w.z = cvt_pk_bf16(v1[0], v1[1]); w.w = cvt_pk_bf16(v1[2], v1[3]);
;                     __builtin_nontemporal_store(w, (u32x4*)(rowp + bj * HALF)); } }
.LBB0_1415:
	s_waitcnt lgkmcnt(0)
	v_pk_mul_f32 v[10:11], v[10:11], v[18:19] op_sel_hi:[1,0]
	v_pk_mul_f32 v[14:15], v[14:15], v[18:19] op_sel_hi:[1,0]
	v_pk_mul_f32 v[12:13], v[12:13], v[18:19] op_sel_hi:[1,0]
	v_max_f32_e32 v10, 0, v10
	v_lshlrev_b64 v[20:21], 7, v[20:21]
	v_pk_mul_f32 v[16:17], v[16:17], v[18:19] op_sel_hi:[1,0]
	v_mul_f32_e32 v19, v10, v10
	v_max_f32_e32 v10, 0, v15
	v_max_f32_e32 v11, 0, v11
	v_max_f32_e32 v12, 0, v12
	v_lshl_add_u64 v[20:21], s[56:57], 0, v[20:21]
	v_max_f32_e32 v14, 0, v14
	v_mul_f32_e32 v10, v10, v10
	v_mul_f32_e32 v15, v11, v11
	v_max_f32_e32 v11, 0, v16
	v_mul_f32_e32 v16, v12, v12
	v_max_f32_e32 v12, 0, v17
	v_max_f32_e32 v13, 0, v13
	v_pk_mul_f32 v[4:5], v[4:5], v[18:19] op_sel_hi:[1,0]
	v_pk_mul_f32 v[2:3], v[2:3], v[18:19] op_sel_hi:[1,0]
	v_lshl_add_u64 v[20:21], v[148:149], 1, v[20:21]
	v_mul_f32_e32 v14, v14, v14
	v_mul_f32_e32 v11, v11, v11
	v_mul_f32_e32 v12, v12, v12
	v_mul_f32_e32 v13, v13, v13
	v_cvt_pk_bf16_f32 v10, v14, v10
	v_pk_mul_f32 v[8:9], v[8:9], v[18:19] op_sel_hi:[1,0]
	v_pk_mul_f32 v[6:7], v[6:7], v[18:19] op_sel_hi:[1,0]
	v_max_f32_e32 v2, 0, v2
	v_max_f32_e32 v3, 0, v3
	v_max_f32_e32 v4, 0, v4
	v_cvt_pk_bf16_f32 v11, v11, v12
	v_cvt_pk_bf16_f32 v12, v19, v15
	v_cvt_pk_bf16_f32 v13, v16, v13
	global_store_dwordx4 v[20:21], v[10:13], off nt
	v_max_f32_e32 v5, 0, v5
	v_max_f32_e32 v6, 0, v6
	v_mul_f32_e32 v10, v2, v2
	v_max_f32_e32 v2, 0, v7
	v_mul_f32_e32 v7, v3, v3
	v_max_f32_e32 v3, 0, v8
	v_mul_f32_e32 v8, v4, v4
	v_max_f32_e32 v4, 0, v9
	v_mul_f32_e32 v2, v2, v2
	v_mul_f32_e32 v3, v3, v3
	v_mul_f32_e32 v4, v4, v4
	v_mul_f32_e32 v5, v5, v5
	s_andn2_b64 vcc, exec, s[16:17]
	s_mov_b64 s[4:5], -1
	v_mul_f32_e32 v6, v6, v6
	v_cvt_pk_bf16_f32 v2, v6, v2
	v_cvt_pk_bf16_f32 v3, v3, v4
	v_cvt_pk_bf16_f32 v4, v10, v7
	v_cvt_pk_bf16_f32 v5, v8, v5
	v_lshl_add_u64 v[252:253], v[20:21], 0, s[58:59]
	global_store_dwordx4 v[252:253], v[2:5], off nt
	s_cbranch_vccnz .LBB0_1375
	s_andn2_b64 vcc, exec, s[6:7]
	s_cbranch_vccnz .LBB0_1374
	s_barrier
	s_branch .LBB0_1374

; #define PG8_STAGE(bufoff, gbase, voff) do { _Pragma("unroll") for (int _i = 0; _i < 2; ++_i) \
;         __builtin_amdgcn_global_load_lds((const unsigned*)((const char*)(gbase) + (voff)[_i]), (PG8_LAS unsigned*)(lds + (bufoff) + ldsw + _i * 8192), 16, 0, 0); } while (0)
; #define PG8_WAIT_V(n) asm volatile("s_waitcnt vmcnt(" #n ")" ::: "memory")
; #define PG8_BAR __builtin_amdgcn_s_barrier()
; template <class Epi, class Sched, bool ALIGN_EPI = false, bool SP2 = false>
; __device__ __forceinline__ void gemm_phase(PG8_LAS unsigned char* lds, const Gemm g, const Sched& S, const Epi& E) {
;     const int tid = threadIdx.x, wid = __builtin_amdgcn_readfirstlane(tid >> 6), lane = tid & 63, wr = wid >> 2, wc = wid & 3, fr = lane & 15, fq = lane >> 4;
;     const int K = g.K, nt = K / BK;
;     unsigned voffA[2], voffB[2];
; #pragma unroll
;     for (int i = 0; i < 2; ++i) { int R, C; stage_rc(tid * 16 + i * 8192, R, C); const int Rb = Epi::PERM ? ((R & ~31) + perm32(R & 31)) : R;
;         voffA[i] = (unsigned)(R * K + C) * 2u; voffB[i] = (unsigned)(Rb * K + C) * 2u; }
;     const size_t kstep = (size_t)(BK * 2);
;     const size_t hstep = (size_t)HALF * K * 2;
;     const size_t tstep = 2 * hstep;
;     const unsigned ldsw = (unsigned)wid * 1024u;
;     const int aoff = lds_byte(wr * 64 + fr, fq * 8), boff = lds_byte(wc * 32 + fr, fq * 8);
;     ...
;     const char* cA = (const char*)g.A + (size_t)cur.pm * tstep; const char* cB = (const char*)g.Bt + (size_t)cur.pn * tstep;
;     S.a_ready(cur);
;     if constexpr (SP2) {
;         PG8_STAGE(PG8_SB(0, 0), cB, voffB); PG8_STAGE(PG8_SB(0, 1), cB + hstep, voffB); PG8_STAGE(PG8_SA(0, 0), cA, voffA); PG8_STAGE(PG8_SA(0, 1), cA + hstep, voffA);
;         if (wr == 1) PG8_BAR;
;         PG8_WAIT_V(2); PG8_BAR;
;         PG8_STAGE(PG8_SB(1, 0), cB + kstep, voffB); PG8_STAGE(PG8_SA(1, 0), cA + kstep, voffA); PG8_STAGE(PG8_SB(1, 1), cB + hstep + kstep, voffB);
; __global__ void __launch_bounds__(NWAVES * 64, 2) mega_fwd(Args args) {
;     ...
;         pg8::Gemm g{F.H, F.Wdn_t, M, D, FF}; pg8::StaticOrder S; S.init(M, D, F.G, (int)blockIdx.x, 1);
.LBB0_1485:
.LBB0_1486:
	s_cmp_lt_i32 s68, 6
	s_cselect_b64 s[0:1], -1, 0
	s_cmp_gt_u32 s33, 5
	s_cselect_b64 s[4:5], -1, 0
	s_and_b64 s[0:1], s[0:1], s[4:5]
	s_andn2_b64 vcc, exec, s[0:1]
	s_cbranch_vccnz .LBB0_1505
	s_abs_i32 s0, s42
	v_cvt_f32_u32_e32 v0, s0
	s_add_i32 s1, s42, 0x2ff
	s_sub_i32 s3, 0xfffffd01, s42
	s_xor_b32 s4, s1, s42
	v_rcp_iflag_f32_e32 v0, v0
	s_max_i32 s1, s1, s3
	s_sub_i32 s3, 0, s0
	s_ashr_i32 s4, s4, 31
	v_mul_f32_e32 v0, 0x4f7ffffe, v0
	v_cvt_u32_f32_e32 v0, v0
	s_nop 0
	v_readfirstlane_b32 s5, v0
	s_mul_i32 s3, s3, s5
	s_mul_hi_u32 s3, s5, s3
	s_add_i32 s5, s5, s3
	s_mul_hi_u32 s3, s1, s5
	s_mul_i32 s5, s3, s0
	s_sub_i32 s1, s1, s5
	s_add_i32 s6, s3, 1
	s_sub_i32 s5, s1, s0
	s_cmp_ge_u32 s1, s0
	s_cselect_b32 s3, s6, s3
	s_cselect_b32 s1, s5, s1
	s_add_i32 s5, s3, 1
	s_cmp_ge_u32 s1, s0
	s_cselect_b32 s0, s5, s3
	s_xor_b32 s0, s0, s4
	s_sub_i32 s3, s0, s4
	s_cmp_lt_i32 s3, 1
	v_readfirstlane_b32 s6, v208
	s_cbranch_scc1 .LBB0_1505
	s_add_i32 s0, s3, -1
	s_ashr_i32 s1, s42, 31
	s_mul_i32 s1, s0, s1
	s_mul_hi_u32 s4, s0, s42
	s_add_i32 s4, s4, s1
	s_mul_i32 s0, s0, s42
	s_ashr_i32 s28, s2, 31
	s_add_u32 s0, s0, s2
	s_addc_u32 s1, s4, s28
	v_mov_b64_e32 v[0:1], 0x2ff
	v_cmp_gt_i64_e32 vcc, s[0:1], v[0:1]
	s_cbranch_vccnz .LBB0_1505
	s_mov_b64 s[70:71], 0x8000
	s_ashr_i32 s5, s0, 31
	s_lshr_b32 s5, s5, 29
	s_add_i32 s5, s0, s5
	s_lshr_b32 s4, s6, 6
	s_ashr_i32 s8, s5, 3
	s_and_b32 s5, s5, -8
	s_lshr_b32 s7, s6, 8
	s_lshl_b32 s29, s4, 10
	s_sub_i32 s0, s0, s5
	s_cmp_lt_i32 s0, 0
	s_movk_i32 s30, 0x61
	s_cselect_b32 s5, s30, 0x60
	s_mul_i32 s0, s0, s5
	s_add_i32 s0, s0, s8
	s_ashr_i32 s5, s0, 31
	s_lshr_b32 s5, s5, 27
	s_add_i32 s5, s0, s5
	v_lshrrev_b32_e32 v2, 1, v208
	s_ashr_i32 s8, s5, 5
	s_waitcnt vmcnt(0)
	v_and_b32_e32 v11, 24, v2
	v_lshrrev_b32_e32 v2, 5, v208
	s_lshl_b32 s8, s8, 3
	v_lshlrev_b32_e32 v0, 4, v208
	v_and_b32_e32 v1, 32, v208
	v_and_b32_e32 v2, 4, v2
	s_waitcnt lgkmcnt(0)
	v_bfe_u32 v3, v208, 2, 2
	s_sub_i32 s9, 0xc0, s8
	v_bfe_u32 v10, v208, 2, 4
	v_bitop3_b32 v8, v0, v1, 48 bitop3:0x6c
	v_and_b32_e32 v9, 64, v208
	v_or3_b32 v2, v2, v3, v11
	v_lshrrev_b32_e32 v3, 3, v208
	s_movk_i32 s1, 0x70
	s_min_i32 s9, s9, 8
	v_or_b32_e32 v1, v8, v9
	v_and_or_b32 v4, v3, s1, v10
	s_abs_i32 s10, s9
	s_movk_i32 s1, 0x60
	v_lshl_or_b32 v128, v4, 7, v1
	v_add_u32_e32 v12, 0x2000, v0
	v_cvt_f32_u32_e32 v4, s10
	v_and_or_b32 v3, v3, s1, v2
	v_lshrrev_b32_e32 v0, 7, v12
	s_movk_i32 s1, 0xf0
	v_lshl_or_b32 v130, v3, 13, v1
	v_and_or_b32 v3, v0, s1, v10
	s_movk_i32 s1, 0xe0
	v_and_or_b32 v0, v0, s1, v2
	v_lshl_or_b32 v134, v0, 13, v1
	v_rcp_iflag_f32_e32 v0, v4
	s_sub_i32 s11, 0, s10
	s_andn2_b32 s5, s5, 31
	s_sub_i32 s0, s0, s5
	v_mul_f32_e32 v0, 0x4f7ffffe, v0
	v_cvt_u32_f32_e32 v0, v0
	s_abs_i32 s5, s0
	s_xor_b32 s1, s0, s9
	s_ashr_i32 s1, s1, 31
	v_readfirstlane_b32 s12, v0
	s_mul_i32 s11, s11, s12
	s_mul_hi_u32 s11, s12, s11
	s_add_i32 s12, s12, s11
	s_mul_hi_u32 s11, s5, s12
	s_mul_i32 s12, s11, s10
	s_sub_i32 s5, s5, s12
	s_add_i32 s12, s11, 1
	s_sub_i32 s13, s5, s10
	s_cmp_ge_u32 s5, s10
	s_cselect_b32 s11, s12, s11
	s_cselect_b32 s5, s13, s5
	s_add_i32 s12, s11, 1
	s_cmp_ge_u32 s5, s10
	s_cselect_b32 s5, s12, s11
	s_xor_b32 s5, s5, s1
	s_sub_i32 s18, s5, s1
	s_mul_i32 s1, s18, s9
	s_sub_i32 s0, s0, s1
	s_add_i32 s20, s8, s0
	s_ashr_i32 s21, s20, 31
	s_ashr_i32 s19, s18, 31
	s_lshl_b64 s[0:1], s[20:21], 21
	s_lshl_b64 s[8:9], s[18:19], 21
	s_add_u32 s24, s64, s8
	s_addc_u32 s25, s65, s9
	s_add_i32 s19, s29, 0x100
	s_add_i32 m0, s19, 0x10000
	v_lshl_or_b32 v132, v3, 7, v1
	global_load_lds_dwordx4 v130, s[24:25]
	s_add_i32 m0, s19, 0x12000
	s_add_u32 s8, s24, 0x100000
	global_load_lds_dwordx4 v134, s[24:25]
	s_addc_u32 s9, s25, 0
	s_add_i32 m0, s19, 0x14000
	v_mov_b32_e32 v131, 0
	global_load_lds_dwordx4 v130, s[8:9]
	s_add_i32 m0, s19, 0x16000
	s_add_u32 s22, s50, s0
	s_addc_u32 s23, s51, s1
	s_add_i32 s21, s19, 0x2000
	global_load_lds_dwordx4 v134, s[8:9]
	s_mov_b32 m0, s19
	s_add_u32 s0, s22, 0x4000
	global_load_lds_dwordx4 v128, s[22:23]
	s_mov_b32 m0, s21
	s_addc_u32 s1, s23, 0
	s_add_i32 s31, s19, 0x4000
	global_load_lds_dwordx4 v132, s[22:23]
	s_mov_b32 m0, s31
	s_add_i32 s33, s19, 0x6000
	global_load_lds_dwordx4 v128, s[0:1]
	s_mov_b32 m0, s33
	v_mov_b32_e32 v135, v131
	global_load_lds_dwordx4 v132, s[0:1]
	v_mov_b32_e32 v129, v131
	v_mov_b32_e32 v133, v131
	s_cmp_eq_u32 s7, 1
	s_mov_b32 s9, 0
	s_mov_b32 s8, 0x10000
	v_lshl_add_u64 v[6:7], s[24:25], 0, v[130:131]
	v_lshl_add_u64 v[2:3], s[24:25], 0, v[134:135]
	s_mov_b32 s10, 0x14000
	v_lshl_add_u64 v[0:1], s[22:23], 0, v[128:129]
	s_cselect_b64 s[0:1], -1, 0
	s_cmp_lg_u32 s7, 1
	v_lshl_add_u64 v[4:5], s[22:23], 0, v[132:133]
	s_cbranch_scc1 .LBB0_1491
	s_barrier
.LBB0_1491:
	s_lshl_b32 s4, s4, 5
	s_and_b32 s14, s4, 0x60
	s_mov_b64 s[4:5], 0x80
	s_add_i32 m0, s19, 0x18000
	v_lshl_add_u64 v[6:7], v[6:7], 0, s[4:5]
	s_lshl_b32 s11, s7, 13
	s_lshl_b32 s15, s14, 7
	s_waitcnt vmcnt(2)
	s_barrier
	global_load_lds_dwordx4 v[6:7], off
	v_lshl_add_u64 v[2:3], v[2:3], 0, s[4:5]
	s_add_i32 m0, s19, 0x1a000
	s_add_i32 s34, s19, 0x8000
	s_add_i32 s35, s19, 0xa000
	global_load_lds_dwordx4 v[2:3], off
	v_lshl_add_u64 v[0:1], v[0:1], 0, s[70:71]
	s_mov_b32 m0, s34
	s_add_u32 s12, s24, 0x100080
	global_load_lds_dwordx4 v[0:1], off
	v_lshl_add_u64 v[0:1], v[4:5], 0, s[70:71]
	s_mov_b32 m0, s35
	s_addc_u32 s13, s25, 0
	global_load_lds_dwordx4 v[0:1], off
	s_add_i32 m0, s19, 0x1c000
	v_lshl_add_u64 v[0:1], s[12:13], 0, v[130:131]
	global_load_lds_dwordx4 v[0:1], off
	v_lshl_add_u64 v[0:1], s[12:13], 0, v[134:135]
	s_add_i32 m0, s19, 0x1e000
	v_lshlrev_b32_e32 v2, 2, v208
	global_load_lds_dwordx4 v[0:1], off
	v_and_b32_e32 v0, 15, v208
	v_lshl_or_b32 v146, s7, 6, v0
	v_lshlrev_b32_e32 v1, 1, v11
	v_lshlrev_b32_e32 v3, 6, v208
	s_movk_i32 s7, 0x3c0
	v_lshl_or_b32 v0, v0, 6, v1
	v_and_b32_e32 v2, 32, v2
	v_and_or_b32 v1, v3, s7, v1
	v_bitop3_b32 v0, v0, s11, v2 bitop3:0xde
	v_bitop3_b32 v1, s15, v1, v2 bitop3:0xf6
	v_lshlrev_b32_e32 v2, 4, v208
	v_and_b32_e32 v2, 0x3800, v2
	v_lshlrev_b32_e32 v3, 7, v10
	v_or3_b32 v2, v8, v2, v3
	v_add_u32_e32 v136, v2, v9
	v_mov_b32_e32 v2, v12
	s_mov_b32 s11, 0x18000
	s_mov_b32 s12, 0x1c000
	s_waitcnt vmcnt(6)
	s_cmpk_lt_u32 s6, 0x100
	v_and_b32_e32 v2, 0x7800, v2
	s_cselect_b64 s[6:7], -1, 0
	v_or3_b32 v2, v8, v2, v3
	s_add_i32 s37, s8, 0x100
	s_add_i32 s38, s10, 0x100
	s_add_i32 s39, s11, 0x100
	s_add_i32 s40, s12, 0x100
	s_add_i32 s36, s3, -2
	v_or_b32_e32 v147, s14, v11
	v_mov_b32_e32 v137, v131
	v_add_u32_e32 v138, v2, v9
	v_mov_b32_e32 v139, v131
	v_add_u32_e32 v148, s37, v1
	v_add_u32_e32 v149, s38, v1
	v_add_u32_e32 v150, 0x100, v0
	v_mov_b64_e32 v[140:141], 0x2ff
	v_add_u32_e32 v151, s39, v1
	v_add_u32_e32 v152, s40, v1
	s_barrier
	s_branch .LBB0_1494

; template <class Epi, class Sched, bool ALIGN_EPI = false, bool SP2 = false>
; __device__ __forceinline__ void gemm_phase(PG8_LAS unsigned char* lds, const Gemm g, const Sched& S, const Epi& E) {
;     ...
;         const bool has_next = S.next(ui + 1, nxt);
;         const char* nA = has_next ? (const char*)g.A + (size_t)nxt.pm * tstep : cA; const char* nB = has_next ? (const char*)g.Bt + (size_t)nxt.pn * tstep : cB;
;         for (int t = 0; t < nt; t += 2) {
;             const bool last = (t == nt - 2);
;             const char* a1 = cA + (size_t)(t + 1) * kstep;
;             const char* a2 = last ? nA : cA + (size_t)(t + 2) * kstep; const char* b2 = last ? nB : cB + (size_t)(t + 2) * kstep;
;             const char* a3 = a2 + kstep; const char* b3 = b2 + kstep;
;             if (last && has_next) S.a_ready(nxt);
;     ...
; #pragma unroll
;         for (int a = 0; a < 2; ++a)
; #pragma unroll
;             for (int b = 0; b < 2; ++b)
; #pragma unroll
;                 for (int m = 0; m < 4; ++m)
; #pragma unroll
;                     for (int n = 0; n < 2; ++n) acc[a][b][m][n] = (f32x4){0.f, 0.f, 0.f, 0.f};
;         cur = nxt; cA = nA; cB = nB; ++ui;
.LBB0_1497:
	s_ashr_i32 s11, s10, 31
	s_lshl_b64 s[12:13], s[10:11], 21
	s_add_u32 s12, s50, s12
	s_addc_u32 s13, s51, s13
	s_and_b64 s[16:17], s[14:15], exec
	s_cselect_b32 s11, s13, s23
	s_cselect_b32 s43, s12, s22
	s_ashr_i32 s9, s8, 31
	s_lshl_b64 s[16:17], s[8:9], 21
	s_add_u32 s16, s64, s16
	s_addc_u32 s17, s65, s17
	s_and_b64 s[26:27], s[14:15], exec
	s_cselect_b32 s9, s17, s25
	s_cselect_b32 s44, s16, s24
	s_add_u32 s22, s22, 0xc000
	s_addc_u32 s23, s23, 0
	s_add_u32 s45, s24, 0x100
	v_mov_b32_e32 v0, 0
	s_addc_u32 s46, s25, 0
	s_mov_b32 s47, -2
	v_mov_b32_e32 v1, v0
	v_mov_b32_e32 v2, v0
	v_mov_b32_e32 v3, v0
	v_mov_b32_e32 v4, v0
	v_mov_b32_e32 v5, v0
	v_mov_b32_e32 v6, v0
	v_mov_b32_e32 v7, v0
	v_mov_b32_e32 v16, v0
	v_mov_b32_e32 v17, v0
	v_mov_b32_e32 v18, v0
	v_mov_b32_e32 v19, v0
	v_mov_b32_e32 v20, v0
	v_mov_b32_e32 v21, v0
	v_mov_b32_e32 v22, v0
	v_mov_b32_e32 v23, v0
	v_mov_b32_e32 v32, v0
	v_mov_b32_e32 v33, v0
	v_mov_b32_e32 v34, v0
	v_mov_b32_e32 v35, v0
	v_mov_b32_e32 v36, v0
	v_mov_b32_e32 v37, v0
	v_mov_b32_e32 v38, v0
	v_mov_b32_e32 v39, v0
	v_mov_b32_e32 v48, v0
	v_mov_b32_e32 v49, v0
	v_mov_b32_e32 v50, v0
	v_mov_b32_e32 v51, v0
	v_mov_b32_e32 v52, v0
	v_mov_b32_e32 v53, v0
	v_mov_b32_e32 v54, v0
	v_mov_b32_e32 v55, v0
	v_mov_b32_e32 v8, v0
	v_mov_b32_e32 v9, v0
	v_mov_b32_e32 v10, v0
	v_mov_b32_e32 v11, v0
	v_mov_b32_e32 v12, v0
	v_mov_b32_e32 v13, v0
	v_mov_b32_e32 v14, v0
	v_mov_b32_e32 v15, v0
	v_mov_b32_e32 v24, v0
	v_mov_b32_e32 v25, v0
	v_mov_b32_e32 v26, v0
	v_mov_b32_e32 v27, v0
	v_mov_b32_e32 v28, v0
	v_mov_b32_e32 v29, v0
	v_mov_b32_e32 v30, v0
	v_mov_b32_e32 v31, v0
	v_mov_b32_e32 v40, v0
	v_mov_b32_e32 v41, v0
	v_mov_b32_e32 v42, v0
	v_mov_b32_e32 v43, v0
	v_mov_b32_e32 v44, v0
	v_mov_b32_e32 v45, v0
	v_mov_b32_e32 v46, v0
	v_mov_b32_e32 v47, v0
	v_mov_b32_e32 v56, v0
	v_mov_b32_e32 v57, v0
	v_mov_b32_e32 v58, v0
	v_mov_b32_e32 v59, v0
	v_mov_b32_e32 v60, v0
	v_mov_b32_e32 v61, v0
	v_mov_b32_e32 v62, v0
	v_mov_b32_e32 v63, v0
	v_mov_b32_e32 v64, v0
	v_mov_b32_e32 v65, v0
	v_mov_b32_e32 v66, v0
	v_mov_b32_e32 v67, v0
	v_mov_b32_e32 v68, v0
	v_mov_b32_e32 v69, v0
	v_mov_b32_e32 v70, v0
	v_mov_b32_e32 v71, v0
	v_mov_b32_e32 v80, v0
	v_mov_b32_e32 v81, v0
	v_mov_b32_e32 v82, v0
	v_mov_b32_e32 v83, v0
	v_mov_b32_e32 v84, v0
	v_mov_b32_e32 v85, v0
	v_mov_b32_e32 v86, v0
	v_mov_b32_e32 v87, v0
	v_mov_b32_e32 v96, v0
	v_mov_b32_e32 v97, v0
	v_mov_b32_e32 v98, v0
	v_mov_b32_e32 v99, v0
	v_mov_b32_e32 v100, v0
	v_mov_b32_e32 v101, v0
	v_mov_b32_e32 v102, v0
	v_mov_b32_e32 v103, v0
	v_mov_b32_e32 v112, v0
	v_mov_b32_e32 v113, v0
	v_mov_b32_e32 v114, v0
	v_mov_b32_e32 v115, v0
	v_mov_b32_e32 v116, v0
	v_mov_b32_e32 v117, v0
	v_mov_b32_e32 v118, v0
	v_mov_b32_e32 v119, v0
	v_mov_b32_e32 v72, v0
	v_mov_b32_e32 v73, v0
	v_mov_b32_e32 v74, v0
	v_mov_b32_e32 v75, v0
	v_mov_b32_e32 v76, v0
	v_mov_b32_e32 v77, v0
	v_mov_b32_e32 v78, v0
	v_mov_b32_e32 v79, v0
	v_mov_b32_e32 v88, v0
	v_mov_b32_e32 v89, v0
	v_mov_b32_e32 v90, v0
	v_mov_b32_e32 v91, v0
	v_mov_b32_e32 v92, v0
	v_mov_b32_e32 v93, v0
	v_mov_b32_e32 v94, v0
	v_mov_b32_e32 v95, v0
	v_mov_b32_e32 v104, v0
	v_mov_b32_e32 v105, v0
	v_mov_b32_e32 v106, v0
	v_mov_b32_e32 v107, v0
	v_mov_b32_e32 v108, v0
	v_mov_b32_e32 v109, v0
	v_mov_b32_e32 v110, v0
	v_mov_b32_e32 v111, v0
	v_mov_b32_e32 v120, v0
	v_mov_b32_e32 v121, v0
	v_mov_b32_e32 v122, v0
	v_mov_b32_e32 v123, v0
	v_mov_b32_e32 v124, v0
	v_mov_b32_e32 v125, v0
	v_mov_b32_e32 v126, v0
	v_mov_b32_e32 v127, v0
.LBB0_1498:
	ds_read_b128 v[142:145], v148
	ds_read_b128 v[154:157], v148 offset:1024
	ds_read_b128 v[158:161], v148 offset:2048
	ds_read_b128 v[162:165], v148 offset:3072
	ds_read_b128 v[166:169], v149
	ds_read_b128 v[170:173], v149 offset:1024
	ds_read_b128 v[174:177], v149 offset:2048
	ds_read_b128 v[178:181], v149 offset:3072
	s_add_u32 s24, s22, 0x4000
	s_addc_u32 s25, s23, 0
	s_cmp_eq_u32 s47, 60
	s_cselect_b32 s27, s11, s25
	s_cselect_b32 s26, s43, s24
	s_cselect_b32 s25, s9, s46
	s_cselect_b32 s24, s44, s45
	v_lshl_add_u64 v[214:215], s[22:23], 0, v[136:137]
	s_add_i32 m0, s19, 0xc000
	ds_read_b128 v[182:185], v150
	ds_read_b128 v[186:189], v150 offset:1024
	ds_read_b128 v[190:193], v150 offset:2048
	ds_read_b128 v[194:197], v150 offset:3072
	ds_read_b128 v[198:201], v150 offset:4096
	ds_read_b128 v[202:205], v150 offset:5120
	ds_read_b128 v[206:209], v150 offset:6144
	ds_read_b128 v[210:213], v150 offset:7168
	global_load_lds_dwordx4 v[214:215], off
	v_lshl_add_u64 v[214:215], s[22:23], 0, v[138:139]
	s_add_i32 m0, s19, 0xe000
	s_nop 0
	global_load_lds_dwordx4 v[214:215], off
	s_waitcnt vmcnt(8)
	s_waitcnt lgkmcnt(0)
	s_barrier
; #define PG8_STAGE(bufoff, gbase, voff) do { _Pragma("unroll") for (int _i = 0; _i < 2; ++_i) \
;         __builtin_amdgcn_global_load_lds((const unsigned*)((const char*)(gbase) + (voff)[_i]), (PG8_LAS unsigned*)(lds + (bufoff) + ldsw + _i * 8192), 16, 0, 0); } while (0)
; #define PG8_LDA(dst, b, h) do { _Pragma("unroll") for (int m = 0; m < 4; ++m) _Pragma("unroll") for (int k = 0; k < 2; ++k) dst[m][k] = *(const PG8_LAS bf16x8*)(lds + PG8_SA(b, h) + aoff + m * 2048 + k * 1024); } while (0)
; #define PG8_MMA(ai, bj, At, Bt) do { __builtin_amdgcn_s_setprio(1); _Pragma("unroll") for (int m = 0; m < 4; ++m) _Pragma("unroll") for (int n = 0; n < 2; ++n) _Pragma("unroll") for (int k = 0; k < 2; ++k) \
;         acc[ai][bj][m][n] = __builtin_amdgcn_mfma_f32_16x16x32_bf16(Bt[n][k], At[m][k], acc[ai][bj][m][n], 0, 0, 0); __builtin_amdgcn_s_setprio(0); } while (0)
; #define PG8_WAIT_V(n) asm volatile("s_waitcnt vmcnt(" #n ")" ::: "memory")
; #define PG8_WAIT_L(n) asm volatile("s_waitcnt lgkmcnt(" #n ")" ::: "memory")
; #define PG8_BAR __builtin_amdgcn_s_barrier()
; #define PG8_SCHED __builtin_amdgcn_sched_barrier(0)
; template <class Epi, class Sched, bool ALIGN_EPI = false, bool SP2 = false>
; __device__ __forceinline__ void gemm_phase(PG8_LAS unsigned char* lds, const Gemm g, const Sched& S, const Epi& E) {
;     ...
;             PG8_WAIT_V(8); PG8_WAIT_L(0); PG8_BAR; PG8_MMA(0, 0, At, B0); PG8_MMA(0, 1, At, B1); PG8_BAR; PG8_SCHED;
;             PG8_LDA(At, 0, 1); PG8_STAGE(PG8_SB(0, 0), b2, voffB); PG8_STAGE(PG8_SB(0, 1), b2 + hstep, voffB); PG8_STAGE(PG8_SA(0, 0), a2, voffA);
;             PG8_WAIT_V(8); PG8_WAIT_L(0); PG8_BAR; PG8_MMA(1, 0, At, B0); PG8_MMA(1, 1, At, B1); PG8_BAR; PG8_SCHED;
	s_setprio 1
	s_waitcnt lgkmcnt(0)
	v_mfma_f32_16x16x32_bf16 v[124:127], v[142:145], v[182:185], v[124:127]
	v_mfma_f32_16x16x32_bf16 v[120:123], v[158:161], v[182:185], v[120:123]
	v_mfma_f32_16x16x32_bf16 v[108:111], v[142:145], v[190:193], v[108:111]
	v_mfma_f32_16x16x32_bf16 v[104:107], v[158:161], v[190:193], v[104:107]
	v_mfma_f32_16x16x32_bf16 v[92:95], v[142:145], v[198:201], v[92:95]
	v_mfma_f32_16x16x32_bf16 v[88:91], v[158:161], v[198:201], v[88:91]
	v_mfma_f32_16x16x32_bf16 v[76:79], v[142:145], v[206:209], v[76:79]
	v_mfma_f32_16x16x32_bf16 v[72:75], v[158:161], v[206:209], v[72:75]
	v_mfma_f32_16x16x32_bf16 v[124:127], v[154:157], v[186:189], v[124:127]
	v_mfma_f32_16x16x32_bf16 v[120:123], v[162:165], v[186:189], v[120:123]
	v_mfma_f32_16x16x32_bf16 v[108:111], v[154:157], v[194:197], v[108:111]
	v_mfma_f32_16x16x32_bf16 v[104:107], v[162:165], v[194:197], v[104:107]
	v_mfma_f32_16x16x32_bf16 v[92:95], v[154:157], v[202:205], v[92:95]
	v_mfma_f32_16x16x32_bf16 v[88:91], v[162:165], v[202:205], v[88:91]
	v_mfma_f32_16x16x32_bf16 v[76:79], v[154:157], v[210:213], v[76:79]
	v_mfma_f32_16x16x32_bf16 v[72:75], v[162:165], v[210:213], v[72:75]
	s_setprio 0
	s_setprio 1
	v_mfma_f32_16x16x32_bf16 v[116:119], v[166:169], v[182:185], v[116:119]
	v_mfma_f32_16x16x32_bf16 v[112:115], v[174:177], v[182:185], v[112:115]
	v_mfma_f32_16x16x32_bf16 v[100:103], v[166:169], v[190:193], v[100:103]
	v_mfma_f32_16x16x32_bf16 v[96:99], v[174:177], v[190:193], v[96:99]
	v_mfma_f32_16x16x32_bf16 v[84:87], v[166:169], v[198:201], v[84:87]
	v_mfma_f32_16x16x32_bf16 v[80:83], v[174:177], v[198:201], v[80:83]
	v_mfma_f32_16x16x32_bf16 v[68:71], v[166:169], v[206:209], v[68:71]
	v_mfma_f32_16x16x32_bf16 v[64:67], v[174:177], v[206:209], v[64:67]
	v_mfma_f32_16x16x32_bf16 v[116:119], v[170:173], v[186:189], v[116:119]
	v_mfma_f32_16x16x32_bf16 v[112:115], v[178:181], v[186:189], v[112:115]
	v_mfma_f32_16x16x32_bf16 v[100:103], v[170:173], v[194:197], v[100:103]
	v_mfma_f32_16x16x32_bf16 v[96:99], v[178:181], v[194:197], v[96:99]
	v_mfma_f32_16x16x32_bf16 v[84:87], v[170:173], v[202:205], v[84:87]
	v_mfma_f32_16x16x32_bf16 v[80:83], v[178:181], v[202:205], v[80:83]
	v_mfma_f32_16x16x32_bf16 v[68:71], v[170:173], v[210:213], v[68:71]
	v_mfma_f32_16x16x32_bf16 v[64:67], v[178:181], v[210:213], v[64:67]
	s_setprio 0
	s_barrier
	s_add_i32 s48, s37, s29
	v_lshl_add_u64 v[214:215], s[24:25], 0, v[130:131]
	s_mov_b32 m0, s48
	ds_read_b128 v[182:185], v150 offset:16384
	ds_read_b128 v[186:189], v150 offset:17408
	ds_read_b128 v[190:193], v150 offset:18432
	ds_read_b128 v[194:197], v150 offset:19456
	ds_read_b128 v[198:201], v150 offset:20480
	ds_read_b128 v[202:205], v150 offset:21504
	ds_read_b128 v[206:209], v150 offset:22528
	ds_read_b128 v[210:213], v150 offset:23552
	global_load_lds_dwordx4 v[214:215], off
	s_add_i32 m0, s48, 0x2000
	s_add_u32 s48, s24, 0x100000
	v_lshl_add_u64 v[216:217], s[24:25], 0, v[134:135]
	s_addc_u32 s49, s25, 0
	s_add_i32 s52, s38, s29
	global_load_lds_dwordx4 v[216:217], off
	v_lshl_add_u64 v[218:219], s[48:49], 0, v[130:131]
	s_mov_b32 m0, s52
	v_lshl_add_u64 v[220:221], s[26:27], 0, v[132:133]
	global_load_lds_dwordx4 v[218:219], off
	v_lshl_add_u64 v[218:219], s[48:49], 0, v[134:135]
	s_add_i32 m0, s52, 0x2000
	s_nop 0
	global_load_lds_dwordx4 v[218:219], off
	v_lshl_add_u64 v[218:219], s[26:27], 0, v[128:129]
	s_mov_b32 m0, s19
	s_nop 0
	global_load_lds_dwordx4 v[218:219], off
	s_mov_b32 m0, s21
	s_nop 0
	global_load_lds_dwordx4 v[220:221], off
	s_waitcnt vmcnt(8)
	s_waitcnt lgkmcnt(0)
	s_barrier
	s_setprio 1
	s_waitcnt lgkmcnt(0)
	v_mfma_f32_16x16x32_bf16 v[60:63], v[142:145], v[182:185], v[60:63]
	v_mfma_f32_16x16x32_bf16 v[56:59], v[158:161], v[182:185], v[56:59]
	v_mfma_f32_16x16x32_bf16 v[44:47], v[142:145], v[190:193], v[44:47]
	v_mfma_f32_16x16x32_bf16 v[40:43], v[158:161], v[190:193], v[40:43]
	v_mfma_f32_16x16x32_bf16 v[28:31], v[142:145], v[198:201], v[28:31]
	v_mfma_f32_16x16x32_bf16 v[24:27], v[158:161], v[198:201], v[24:27]
	v_mfma_f32_16x16x32_bf16 v[12:15], v[142:145], v[206:209], v[12:15]
	v_mfma_f32_16x16x32_bf16 v[8:11], v[158:161], v[206:209], v[8:11]
	v_mfma_f32_16x16x32_bf16 v[60:63], v[154:157], v[186:189], v[60:63]
	v_mfma_f32_16x16x32_bf16 v[56:59], v[162:165], v[186:189], v[56:59]
	v_mfma_f32_16x16x32_bf16 v[44:47], v[154:157], v[194:197], v[44:47]
	v_mfma_f32_16x16x32_bf16 v[40:43], v[162:165], v[194:197], v[40:43]
	v_mfma_f32_16x16x32_bf16 v[28:31], v[154:157], v[202:205], v[28:31]
	v_mfma_f32_16x16x32_bf16 v[24:27], v[162:165], v[202:205], v[24:27]
	v_mfma_f32_16x16x32_bf16 v[12:15], v[154:157], v[210:213], v[12:15]
	v_mfma_f32_16x16x32_bf16 v[8:11], v[162:165], v[210:213], v[8:11]
	s_setprio 0
	s_setprio 1
	v_mfma_f32_16x16x32_bf16 v[52:55], v[166:169], v[182:185], v[52:55]
	v_mfma_f32_16x16x32_bf16 v[48:51], v[174:177], v[182:185], v[48:51]
	v_mfma_f32_16x16x32_bf16 v[36:39], v[166:169], v[190:193], v[36:39]
	v_mfma_f32_16x16x32_bf16 v[32:35], v[174:177], v[190:193], v[32:35]
	v_mfma_f32_16x16x32_bf16 v[20:23], v[166:169], v[198:201], v[20:23]
	v_mfma_f32_16x16x32_bf16 v[16:19], v[174:177], v[198:201], v[16:19]
	v_mfma_f32_16x16x32_bf16 v[4:7], v[166:169], v[206:209], v[4:7]
	v_mfma_f32_16x16x32_bf16 v[0:3], v[174:177], v[206:209], v[0:3]
	v_mfma_f32_16x16x32_bf16 v[52:55], v[170:173], v[186:189], v[52:55]
	v_mfma_f32_16x16x32_bf16 v[48:51], v[178:181], v[186:189], v[48:51]
	v_mfma_f32_16x16x32_bf16 v[36:39], v[170:173], v[194:197], v[36:39]
	v_mfma_f32_16x16x32_bf16 v[32:35], v[178:181], v[194:197], v[32:35]
	v_mfma_f32_16x16x32_bf16 v[20:23], v[170:173], v[202:205], v[20:23]
	v_mfma_f32_16x16x32_bf16 v[16:19], v[178:181], v[202:205], v[16:19]
	v_mfma_f32_16x16x32_bf16 v[4:7], v[170:173], v[210:213], v[4:7]
	v_mfma_f32_16x16x32_bf16 v[0:3], v[178:181], v[210:213], v[0:3]
	s_setprio 0
	s_barrier
; #define PG8_STAGE(bufoff, gbase, voff) do { _Pragma("unroll") for (int _i = 0; _i < 2; ++_i) \
;         __builtin_amdgcn_global_load_lds((const unsigned*)((const char*)(gbase) + (voff)[_i]), (PG8_LAS unsigned*)(lds + (bufoff) + ldsw + _i * 8192), 16, 0, 0); } while (0)
; #define PG8_LDA(dst, b, h) do { _Pragma("unroll") for (int m = 0; m < 4; ++m) _Pragma("unroll") for (int k = 0; k < 2; ++k) dst[m][k] = *(const PG8_LAS bf16x8*)(lds + PG8_SA(b, h) + aoff + m * 2048 + k * 1024); } while (0)
; #define PG8_LDB(dst, b, h) do { _Pragma("unroll") for (int n = 0; n < 2; ++n) _Pragma("unroll") for (int k = 0; k < 2; ++k) dst[n][k] = *(const PG8_LAS bf16x8*)(lds + PG8_SB(b, h) + boff + n * 2048 + k * 1024); } while (0)
; #define PG8_MMA(ai, bj, At, Bt) do { __builtin_amdgcn_s_setprio(1); _Pragma("unroll") for (int m = 0; m < 4; ++m) _Pragma("unroll") for (int n = 0; n < 2; ++n) _Pragma("unroll") for (int k = 0; k < 2; ++k) \
;         acc[ai][bj][m][n] = __builtin_amdgcn_mfma_f32_16x16x32_bf16(Bt[n][k], At[m][k], acc[ai][bj][m][n], 0, 0, 0); __builtin_amdgcn_s_setprio(0); } while (0)
; #define PG8_WAIT_V(n) asm volatile("s_waitcnt vmcnt(" #n ")" ::: "memory")
; #define PG8_WAIT_L(n) asm volatile("s_waitcnt lgkmcnt(" #n ")" ::: "memory")
; #define PG8_BAR __builtin_amdgcn_s_barrier()
; #define PG8_SCHED __builtin_amdgcn_sched_barrier(0)
; template <class Epi, class Sched, bool ALIGN_EPI = false, bool SP2 = false>
; __device__ __forceinline__ void gemm_phase(PG8_LAS unsigned char* lds, const Gemm g, const Sched& S, const Epi& E) {
;     ...
;             PG8_LDB(B0, 1, 0); PG8_LDB(B1, 1, 1); PG8_SCHED; PG8_LDA(At, 1, 0); PG8_STAGE(PG8_SA(0, 1), a2 + hstep, voffA);
;             PG8_WAIT_V(8); PG8_WAIT_L(0); PG8_BAR; PG8_MMA(0, 0, At, B0); PG8_MMA(0, 1, At, B1); PG8_BAR; PG8_SCHED;
	ds_read_b128 v[142:145], v151
	ds_read_b128 v[154:157], v151 offset:1024
	ds_read_b128 v[158:161], v151 offset:2048
	ds_read_b128 v[162:165], v151 offset:3072
	ds_read_b128 v[166:169], v152
	ds_read_b128 v[170:173], v152 offset:1024
	ds_read_b128 v[174:177], v152 offset:2048
	ds_read_b128 v[178:181], v152 offset:3072
	s_add_u32 s26, s26, 0x4000
	s_addc_u32 s27, s27, 0
	s_mov_b32 m0, s31
	v_lshl_add_u64 v[222:223], s[26:27], 0, v[128:129]
	ds_read_b128 v[182:185], v150 offset:32768
	ds_read_b128 v[186:189], v150 offset:33792
	ds_read_b128 v[190:193], v150 offset:34816
	ds_read_b128 v[194:197], v150 offset:35840
	ds_read_b128 v[198:201], v150 offset:36864
	ds_read_b128 v[202:205], v150 offset:37888
	ds_read_b128 v[206:209], v150 offset:38912
	ds_read_b128 v[210:213], v150 offset:39936
	global_load_lds_dwordx4 v[222:223], off
	v_lshl_add_u64 v[222:223], s[26:27], 0, v[132:133]
	s_mov_b32 m0, s33
	s_nop 0
	global_load_lds_dwordx4 v[222:223], off
	s_waitcnt vmcnt(8)
	s_waitcnt lgkmcnt(0)
	s_barrier
	s_setprio 1
	s_waitcnt lgkmcnt(0)
	v_mfma_f32_16x16x32_bf16 v[124:127], v[142:145], v[182:185], v[124:127]
	v_mfma_f32_16x16x32_bf16 v[120:123], v[158:161], v[182:185], v[120:123]
	v_mfma_f32_16x16x32_bf16 v[108:111], v[142:145], v[190:193], v[108:111]
	v_mfma_f32_16x16x32_bf16 v[104:107], v[158:161], v[190:193], v[104:107]
	v_mfma_f32_16x16x32_bf16 v[92:95], v[142:145], v[198:201], v[92:95]
	v_mfma_f32_16x16x32_bf16 v[88:91], v[158:161], v[198:201], v[88:91]
	v_mfma_f32_16x16x32_bf16 v[76:79], v[142:145], v[206:209], v[76:79]
	v_mfma_f32_16x16x32_bf16 v[72:75], v[158:161], v[206:209], v[72:75]
	v_mfma_f32_16x16x32_bf16 v[124:127], v[154:157], v[186:189], v[124:127]
	v_mfma_f32_16x16x32_bf16 v[120:123], v[162:165], v[186:189], v[120:123]
	v_mfma_f32_16x16x32_bf16 v[108:111], v[154:157], v[194:197], v[108:111]
	v_mfma_f32_16x16x32_bf16 v[104:107], v[162:165], v[194:197], v[104:107]
	v_mfma_f32_16x16x32_bf16 v[92:95], v[154:157], v[202:205], v[92:95]
	v_mfma_f32_16x16x32_bf16 v[88:91], v[162:165], v[202:205], v[88:91]
	v_mfma_f32_16x16x32_bf16 v[76:79], v[154:157], v[210:213], v[76:79]
	v_mfma_f32_16x16x32_bf16 v[72:75], v[162:165], v[210:213], v[72:75]
	s_setprio 0
	s_setprio 1
	v_mfma_f32_16x16x32_bf16 v[116:119], v[166:169], v[182:185], v[116:119]
	v_mfma_f32_16x16x32_bf16 v[112:115], v[174:177], v[182:185], v[112:115]
	v_mfma_f32_16x16x32_bf16 v[100:103], v[166:169], v[190:193], v[100:103]
	v_mfma_f32_16x16x32_bf16 v[96:99], v[174:177], v[190:193], v[96:99]
	v_mfma_f32_16x16x32_bf16 v[84:87], v[166:169], v[198:201], v[84:87]
	v_mfma_f32_16x16x32_bf16 v[80:83], v[174:177], v[198:201], v[80:83]
	v_mfma_f32_16x16x32_bf16 v[68:71], v[166:169], v[206:209], v[68:71]
	v_mfma_f32_16x16x32_bf16 v[64:67], v[174:177], v[206:209], v[64:67]
	v_mfma_f32_16x16x32_bf16 v[116:119], v[170:173], v[186:189], v[116:119]
	v_mfma_f32_16x16x32_bf16 v[112:115], v[178:181], v[186:189], v[112:115]
	v_mfma_f32_16x16x32_bf16 v[100:103], v[170:173], v[194:197], v[100:103]
	v_mfma_f32_16x16x32_bf16 v[96:99], v[178:181], v[194:197], v[96:99]
	v_mfma_f32_16x16x32_bf16 v[84:87], v[170:173], v[202:205], v[84:87]
	v_mfma_f32_16x16x32_bf16 v[80:83], v[178:181], v[202:205], v[80:83]
	v_mfma_f32_16x16x32_bf16 v[68:71], v[170:173], v[210:213], v[68:71]
	v_mfma_f32_16x16x32_bf16 v[64:67], v[178:181], v[210:213], v[64:67]
	s_setprio 0
	s_barrier
; #define PG8_STAGE(bufoff, gbase, voff) do { _Pragma("unroll") for (int _i = 0; _i < 2; ++_i) \
;         __builtin_amdgcn_global_load_lds((const unsigned*)((const char*)(gbase) + (voff)[_i]), (PG8_LAS unsigned*)(lds + (bufoff) + ldsw + _i * 8192), 16, 0, 0); } while (0)
; #define PG8_LDA(dst, b, h) do { _Pragma("unroll") for (int m = 0; m < 4; ++m) _Pragma("unroll") for (int k = 0; k < 2; ++k) dst[m][k] = *(const PG8_LAS bf16x8*)(lds + PG8_SA(b, h) + aoff + m * 2048 + k * 1024); } while (0)
; #define PG8_MMA(ai, bj, At, Bt) do { __builtin_amdgcn_s_setprio(1); _Pragma("unroll") for (int m = 0; m < 4; ++m) _Pragma("unroll") for (int n = 0; n < 2; ++n) _Pragma("unroll") for (int k = 0; k < 2; ++k) \
;         acc[ai][bj][m][n] = __builtin_amdgcn_mfma_f32_16x16x32_bf16(Bt[n][k], At[m][k], acc[ai][bj][m][n], 0, 0, 0); __builtin_amdgcn_s_setprio(0); } while (0)
; #define PG8_WAIT_V(n) asm volatile("s_waitcnt vmcnt(" #n ")" ::: "memory")
; #define PG8_WAIT_L(n) asm volatile("s_waitcnt lgkmcnt(" #n ")" ::: "memory")
; #define PG8_BAR __builtin_amdgcn_s_barrier()
; #define PG8_SCHED __builtin_amdgcn_sched_barrier(0)
; template <class Epi, class Sched, bool ALIGN_EPI = false, bool SP2 = false>
; __device__ __forceinline__ void gemm_phase(PG8_LAS unsigned char* lds, const Gemm g, const Sched& S, const Epi& E) {
;     ...
;             PG8_LDA(At, 1, 1); PG8_STAGE(PG8_SB(1, 0), b3, voffB); PG8_STAGE(PG8_SB(1, 1), b3 + hstep, voffB); PG8_STAGE(PG8_SA(1, 0), a3, voffA);
;             PG8_WAIT_V(8); PG8_WAIT_L(0); PG8_BAR; PG8_MMA(1, 0, At, B0); PG8_MMA(1, 1, At, B1); PG8_BAR; PG8_SCHED;
	s_add_i32 s26, s39, s29
	v_lshl_add_u64 v[214:215], v[214:215], 0, s[4:5]
	s_mov_b32 m0, s26
	ds_read_b128 v[182:185], v150 offset:49152
	ds_read_b128 v[186:189], v150 offset:50176
	ds_read_b128 v[190:193], v150 offset:51200
	ds_read_b128 v[194:197], v150 offset:52224
	ds_read_b128 v[198:201], v150 offset:53248
	ds_read_b128 v[202:205], v150 offset:54272
	ds_read_b128 v[206:209], v150 offset:55296
	ds_read_b128 v[210:213], v150 offset:56320
	global_load_lds_dwordx4 v[214:215], off
	s_add_i32 m0, s26, 0x2000
	s_add_u32 s24, s24, 0x100080
	v_lshl_add_u64 v[214:215], v[216:217], 0, s[4:5]
	s_addc_u32 s25, s25, 0
	s_add_i32 s26, s40, s29
	global_load_lds_dwordx4 v[214:215], off
	v_lshl_add_u64 v[214:215], s[24:25], 0, v[130:131]
	s_mov_b32 m0, s26
	s_nop 0
	global_load_lds_dwordx4 v[214:215], off
	v_lshl_add_u64 v[214:215], s[24:25], 0, v[134:135]
	s_add_i32 m0, s26, 0x2000
	s_nop 0
	global_load_lds_dwordx4 v[214:215], off
	v_lshl_add_u64 v[214:215], v[218:219], 0, s[70:71]
	s_mov_b32 m0, s34
	s_nop 0
	global_load_lds_dwordx4 v[214:215], off
	v_lshl_add_u64 v[214:215], v[220:221], 0, s[70:71]
	s_mov_b32 m0, s35
	s_nop 0
	global_load_lds_dwordx4 v[214:215], off
	s_waitcnt vmcnt(8)
	s_waitcnt lgkmcnt(0)
	s_barrier
	s_setprio 1
	s_waitcnt lgkmcnt(0)
	v_mfma_f32_16x16x32_bf16 v[60:63], v[142:145], v[182:185], v[60:63]
	v_mfma_f32_16x16x32_bf16 v[56:59], v[158:161], v[182:185], v[56:59]
	v_mfma_f32_16x16x32_bf16 v[44:47], v[142:145], v[190:193], v[44:47]
	v_mfma_f32_16x16x32_bf16 v[40:43], v[158:161], v[190:193], v[40:43]
	v_mfma_f32_16x16x32_bf16 v[28:31], v[142:145], v[198:201], v[28:31]
	v_mfma_f32_16x16x32_bf16 v[24:27], v[158:161], v[198:201], v[24:27]
	v_mfma_f32_16x16x32_bf16 v[12:15], v[142:145], v[206:209], v[12:15]
	v_mfma_f32_16x16x32_bf16 v[8:11], v[158:161], v[206:209], v[8:11]
	v_mfma_f32_16x16x32_bf16 v[60:63], v[154:157], v[186:189], v[60:63]
	v_mfma_f32_16x16x32_bf16 v[56:59], v[162:165], v[186:189], v[56:59]
	v_mfma_f32_16x16x32_bf16 v[44:47], v[154:157], v[194:197], v[44:47]
	v_mfma_f32_16x16x32_bf16 v[40:43], v[162:165], v[194:197], v[40:43]
	v_mfma_f32_16x16x32_bf16 v[28:31], v[154:157], v[202:205], v[28:31]
	v_mfma_f32_16x16x32_bf16 v[24:27], v[162:165], v[202:205], v[24:27]
	v_mfma_f32_16x16x32_bf16 v[12:15], v[154:157], v[210:213], v[12:15]
	v_mfma_f32_16x16x32_bf16 v[8:11], v[162:165], v[210:213], v[8:11]
	s_setprio 0
	s_setprio 1
	v_mfma_f32_16x16x32_bf16 v[52:55], v[166:169], v[182:185], v[52:55]
	v_mfma_f32_16x16x32_bf16 v[48:51], v[174:177], v[182:185], v[48:51]
	v_mfma_f32_16x16x32_bf16 v[36:39], v[166:169], v[190:193], v[36:39]
	v_mfma_f32_16x16x32_bf16 v[32:35], v[174:177], v[190:193], v[32:35]
	v_mfma_f32_16x16x32_bf16 v[20:23], v[166:169], v[198:201], v[20:23]
	v_mfma_f32_16x16x32_bf16 v[16:19], v[174:177], v[198:201], v[16:19]
	v_mfma_f32_16x16x32_bf16 v[4:7], v[166:169], v[206:209], v[4:7]
	v_mfma_f32_16x16x32_bf16 v[0:3], v[174:177], v[206:209], v[0:3]
	v_mfma_f32_16x16x32_bf16 v[52:55], v[170:173], v[186:189], v[52:55]
	v_mfma_f32_16x16x32_bf16 v[48:51], v[178:181], v[186:189], v[48:51]
	v_mfma_f32_16x16x32_bf16 v[36:39], v[170:173], v[194:197], v[36:39]
	v_mfma_f32_16x16x32_bf16 v[32:35], v[178:181], v[194:197], v[32:35]
	v_mfma_f32_16x16x32_bf16 v[20:23], v[170:173], v[202:205], v[20:23]
	v_mfma_f32_16x16x32_bf16 v[16:19], v[178:181], v[202:205], v[16:19]
	v_mfma_f32_16x16x32_bf16 v[4:7], v[170:173], v[210:213], v[4:7]
	v_mfma_f32_16x16x32_bf16 v[0:3], v[178:181], v[210:213], v[0:3]
	s_setprio 0
	s_barrier
	s_add_i32 s47, s47, 2
	s_add_u32 s22, s22, 0x10000
	s_addc_u32 s23, s23, 0
	s_add_u32 s45, s45, 0x100
	s_addc_u32 s46, s46, 0
	s_cmp_gt_u32 s47, 61
	s_cbranch_scc0 .LBB0_1498
	s_and_b64 vcc, exec, s[6:7]
	s_cbranch_vccz .LBB0_1501
	s_barrier
